# mid-segment priority toggle removed so the other wave's early accumulate chain is not split by this wave's MFMA stream
# speedup vs baseline: 1.0085x; 1.0085x over previous
; #define PG8_STAGE(bufoff, gbase, voff) do { _Pragma("unroll") for (int _i = 0; _i < 2; ++_i) \
;         __builtin_amdgcn_global_load_lds((const unsigned*)((const char*)(gbase) + (voff)[_i]), (PG8_LAS unsigned*)(lds + (bufoff) + ldsw + _i * 8192), 16, 0, 0); } while (0)
; #define PG8_LDA(dst, b, h) do { _Pragma("unroll") for (int m = 0; m < 4; ++m) _Pragma("unroll") for (int k = 0; k < 2; ++k) dst[m][k] = *(const PG8_LAS bf16x8*)(lds + PG8_SA(b, h) + aoff + m * 2048 + k * 1024); } while (0)
; #define PG8_LDB(dst, b, h) do { _Pragma("unroll") for (int n = 0; n < 2; ++n) _Pragma("unroll") for (int k = 0; k < 2; ++k) dst[n][k] = *(const PG8_LAS bf16x8*)(lds + PG8_SB(b, h) + boff + n * 2048 + k * 1024); } while (0)
; #define PG8_MMA(ai, bj, At, Bt) do { __builtin_amdgcn_s_setprio(1); _Pragma("unroll") for (int m = 0; m < 4; ++m) _Pragma("unroll") for (int n = 0; n < 2; ++n) _Pragma("unroll") for (int k = 0; k < 2; ++k) \
;         acc[ai][bj][m][n] = __builtin_amdgcn_mfma_f32_16x16x32_bf16(Bt[n][k], At[m][k], acc[ai][bj][m][n], 0, 0, 0); __builtin_amdgcn_s_setprio(0); } while (0)
; #define PG8_WAIT_V(n) asm volatile("s_waitcnt vmcnt(" #n ")" ::: "memory")
; #define PG8_BAR __builtin_amdgcn_s_barrier()
; template <class Epi, class Sched, bool ALIGN_EPI = false, bool SP2 = false, bool ABLK = false, bool BBLK = false>
; __device__ __forceinline__ void gemm_phase(PG8_LAS unsigned char* lds, const Gemm g, const Sched& S, const Epi& E) {
;     ...
;             const bool last = (t == nt - 2);
;             const char* a1 = cA + (size_t)(t + 1) * kstepA;
;             const char* a2 = last ? nA : cA + (size_t)(t + 2) * kstepA; const char* b2 = last ? nB : cB + (size_t)(t + 2) * kstepB;
;             const char* a3 = a2 + kstepA; const char* b3 = b2 + kstepB;
;             if (last && has_next) S.a_ready(nxt);
;             if constexpr (SP2) {
;             PG8_LDB(B0, 0, 0); PG8_LDB(B1, 0, 1); PG8_SCHED; PG8_LDA(At, 0, 0); PG8_STAGE(PG8_SA(1, 1), a1 + hstepA, voffA);
;             PG8_WAIT_V(8); PG8_WAIT_L(0); PG8_BAR; PG8_MMA(0, 0, At, B0); PG8_MMA(0, 1, At, B1); PG8_BAR; PG8_SCHED;
;             PG8_LDA(At, 0, 1); PG8_STAGE(PG8_SB(0, 0), b2, voffB); PG8_STAGE(PG8_SB(0, 1), b2 + hstepB, voffB); PG8_STAGE(PG8_SA(0, 0), a2, voffA);
;             PG8_WAIT_V(8); PG8_WAIT_L(0); PG8_BAR; PG8_MMA(1, 0, At, B0); PG8_MMA(1, 1, At, B1); PG8_BAR; PG8_SCHED;
.LBB0_185:
	s_add_u32 s13, s20, 0x4000
	s_addc_u32 s22, s21, 0
	s_cmp_eq_u32 vcc_hi, 28
	s_cselect_b32 s26, s70, s13
	s_cselect_b32 s27, s9, s22
	s_cselect_b32 s24, s71, s77
	s_cselect_b32 s25, s7, vcc_lo
	s_add_u32 s22, s26, 0x8000
	s_addc_u32 s23, s27, 0
	s_add_i32 s13, 0, 0x10000
	v_add_u32_e32 v36, s13, v160
	s_add_i32 s88, 0, 0x14000
	ds_read_b128 v[152:155], v36
	ds_read_b128 v[156:159], v36 offset:1024
	ds_read_b128 v[162:165], v36 offset:2048
	ds_read_b128 v[166:169], v36 offset:3072
	v_add_u32_e32 v36, s88, v160
	ds_read_b128 v[170:173], v36
	ds_read_b128 v[174:177], v36 offset:1024
	ds_read_b128 v[178:181], v36 offset:2048
	ds_read_b128 v[182:185], v36 offset:3072
	s_add_i32 m0, s19, 0xc000
	ds_read_b128 v[186:189], v161
	ds_read_b128 v[190:193], v161 offset:1024
	ds_read_b128 v[194:197], v161 offset:2048
	ds_read_b128 v[198:201], v161 offset:3072
	ds_read_b128 v[202:205], v161 offset:4096
	ds_read_b128 v[206:209], v161 offset:5120
	ds_read_b128 v[210:213], v161 offset:6144
	ds_read_b128 v[214:217], v161 offset:7168
	global_load_lds_dwordx4 v148, s[20:21]
	s_add_i32 m0, s19, 0xe000
	s_nop 0
	global_load_lds_dwordx4 v150, s[20:21]
	s_waitcnt vmcnt(8)
	s_waitcnt lgkmcnt(0)
	v_mfma_f32_16x16x32_bf16 v[132:135], v[152:155], v[186:189], v[132:135]
	v_mfma_f32_16x16x32_bf16 v[132:135], v[156:159], v[190:193], v[132:135]
	v_mfma_f32_16x16x32_bf16 v[128:131], v[166:169], v[190:193], v[128:131]
	v_mfma_f32_16x16x32_bf16 v[128:131], v[162:165], v[186:189], v[128:131]
	s_barrier
	s_setprio 1
	v_mfma_f32_16x16x32_bf16 v[112:115], v[162:165], v[194:197], v[112:115]
	v_mfma_f32_16x16x32_bf16 v[112:115], v[166:169], v[198:201], v[112:115]
	v_mfma_f32_16x16x32_bf16 v[116:119], v[156:159], v[198:201], v[116:119]
	v_mfma_f32_16x16x32_bf16 v[116:119], v[152:155], v[194:197], v[116:119]
	v_mfma_f32_16x16x32_bf16 v[100:103], v[152:155], v[202:205], v[100:103]
	v_mfma_f32_16x16x32_bf16 v[100:103], v[156:159], v[206:209], v[100:103]
	v_mfma_f32_16x16x32_bf16 v[96:99], v[166:169], v[206:209], v[96:99]
	v_mfma_f32_16x16x32_bf16 v[96:99], v[162:165], v[202:205], v[96:99]
	v_mfma_f32_16x16x32_bf16 v[80:83], v[162:165], v[210:213], v[80:83]
	v_mfma_f32_16x16x32_bf16 v[80:83], v[166:169], v[214:217], v[80:83]
	v_mfma_f32_16x16x32_bf16 v[84:87], v[156:159], v[214:217], v[84:87]
	v_mfma_f32_16x16x32_bf16 v[84:87], v[152:155], v[210:213], v[84:87]
	v_mfma_f32_16x16x32_bf16 v[76:79], v[170:173], v[210:213], v[76:79]
	v_mfma_f32_16x16x32_bf16 v[76:79], v[174:177], v[214:217], v[76:79]
	v_mfma_f32_16x16x32_bf16 v[124:127], v[174:177], v[190:193], v[124:127]
	v_mfma_f32_16x16x32_bf16 v[124:127], v[170:173], v[186:189], v[124:127]
	v_mfma_f32_16x16x32_bf16 v[120:123], v[178:181], v[186:189], v[120:123]
	v_mfma_f32_16x16x32_bf16 v[120:123], v[182:185], v[190:193], v[120:123]
	v_mfma_f32_16x16x32_bf16 v[104:107], v[182:185], v[198:201], v[104:107]
	v_mfma_f32_16x16x32_bf16 v[104:107], v[178:181], v[194:197], v[104:107]
	v_mfma_f32_16x16x32_bf16 v[108:111], v[170:173], v[194:197], v[108:111]
	v_mfma_f32_16x16x32_bf16 v[108:111], v[174:177], v[198:201], v[108:111]
	v_mfma_f32_16x16x32_bf16 v[92:95], v[174:177], v[206:209], v[92:95]
	v_mfma_f32_16x16x32_bf16 v[92:95], v[170:173], v[202:205], v[92:95]
	v_mfma_f32_16x16x32_bf16 v[88:91], v[178:181], v[202:205], v[88:91]
	v_mfma_f32_16x16x32_bf16 v[88:91], v[182:185], v[206:209], v[88:91]
	v_mfma_f32_16x16x32_bf16 v[72:75], v[182:185], v[214:217], v[72:75]
	v_mfma_f32_16x16x32_bf16 v[72:75], v[178:181], v[210:213], v[72:75]
	s_setprio 0
	s_barrier
	s_add_i32 s13, s13, s31
	s_mov_b32 m0, s13
	ds_read_b128 v[186:189], v161 offset:16384
	ds_read_b128 v[190:193], v161 offset:17408
	ds_read_b128 v[194:197], v161 offset:18432
	ds_read_b128 v[198:201], v161 offset:19456
	ds_read_b128 v[202:205], v161 offset:20480
	ds_read_b128 v[206:209], v161 offset:21504
	ds_read_b128 v[210:213], v161 offset:22528
	ds_read_b128 v[214:217], v161 offset:23552
	global_load_lds_dwordx4 v140, s[24:25]
	s_add_i32 m0, s13, 0x2000
	s_add_u32 s68, s24, 0x4000
	s_addc_u32 s69, s25, 0
	s_add_i32 s13, s88, s31
	global_load_lds_dwordx4 v136, s[24:25]
	s_mov_b32 m0, s13
	s_nop 0
	global_load_lds_dwordx4 v140, s[68:69]
	s_add_i32 m0, s13, 0x2000
	s_nop 0
	global_load_lds_dwordx4 v136, s[68:69]
	s_mov_b32 m0, s19
	s_nop 0
	global_load_lds_dwordx4 v142, s[26:27]
	s_mov_b32 m0, s35
	s_nop 0
	global_load_lds_dwordx4 v138, s[26:27]
	s_waitcnt vmcnt(8)
	s_waitcnt lgkmcnt(0)
	v_mfma_f32_16x16x32_bf16 v[68:71], v[152:155], v[186:189], v[68:71]
	v_mfma_f32_16x16x32_bf16 v[68:71], v[156:159], v[190:193], v[68:71]
	v_mfma_f32_16x16x32_bf16 v[64:67], v[166:169], v[190:193], v[64:67]
	v_mfma_f32_16x16x32_bf16 v[64:67], v[162:165], v[186:189], v[64:67]
	s_barrier
; #define PG8_STAGE(bufoff, gbase, voff) do { _Pragma("unroll") for (int _i = 0; _i < 2; ++_i) \
;         __builtin_amdgcn_global_load_lds((const unsigned*)((const char*)(gbase) + (voff)[_i]), (PG8_LAS unsigned*)(lds + (bufoff) + ldsw + _i * 8192), 16, 0, 0); } while (0)
; #define PG8_LDA(dst, b, h) do { _Pragma("unroll") for (int m = 0; m < 4; ++m) _Pragma("unroll") for (int k = 0; k < 2; ++k) dst[m][k] = *(const PG8_LAS bf16x8*)(lds + PG8_SA(b, h) + aoff + m * 2048 + k * 1024); } while (0)
; #define PG8_LDB(dst, b, h) do { _Pragma("unroll") for (int n = 0; n < 2; ++n) _Pragma("unroll") for (int k = 0; k < 2; ++k) dst[n][k] = *(const PG8_LAS bf16x8*)(lds + PG8_SB(b, h) + boff + n * 2048 + k * 1024); } while (0)
; #define PG8_MMA(ai, bj, At, Bt) do { __builtin_amdgcn_s_setprio(1); _Pragma("unroll") for (int m = 0; m < 4; ++m) _Pragma("unroll") for (int n = 0; n < 2; ++n) _Pragma("unroll") for (int k = 0; k < 2; ++k) \
;         acc[ai][bj][m][n] = __builtin_amdgcn_mfma_f32_16x16x32_bf16(Bt[n][k], At[m][k], acc[ai][bj][m][n], 0, 0, 0); __builtin_amdgcn_s_setprio(0); } while (0)
; #define PG8_WAIT_V(n) asm volatile("s_waitcnt vmcnt(" #n ")" ::: "memory")
; #define PG8_WAIT_L(n) asm volatile("s_waitcnt lgkmcnt(" #n ")" ::: "memory")
; #define PG8_BAR __builtin_amdgcn_s_barrier()
; #define PG8_SCHED __builtin_amdgcn_sched_barrier(0)
; template <class Epi, class Sched, bool ALIGN_EPI = false, bool SP2 = false, bool ABLK = false, bool BBLK = false>
; __device__ __forceinline__ void gemm_phase(PG8_LAS unsigned char* lds, const Gemm g, const Sched& S, const Epi& E) {
;     ...
;             PG8_WAIT_V(8); PG8_WAIT_L(0); PG8_BAR; PG8_MMA(1, 0, At, B0); PG8_MMA(1, 1, At, B1); PG8_BAR; PG8_SCHED;
;             PG8_LDB(B0, 1, 0); PG8_LDB(B1, 1, 1); PG8_SCHED; PG8_LDA(At, 1, 0); PG8_STAGE(PG8_SA(0, 1), a2 + hstepA, voffA);
;             PG8_WAIT_V(8); PG8_WAIT_L(0); PG8_BAR; PG8_MMA(0, 0, At, B0); PG8_MMA(0, 1, At, B1); PG8_BAR; PG8_SCHED;
	s_setprio 1
	v_mfma_f32_16x16x32_bf16 v[48:51], v[162:165], v[194:197], v[48:51]
	v_mfma_f32_16x16x32_bf16 v[48:51], v[166:169], v[198:201], v[48:51]
	v_mfma_f32_16x16x32_bf16 v[52:55], v[156:159], v[198:201], v[52:55]
	v_mfma_f32_16x16x32_bf16 v[52:55], v[152:155], v[194:197], v[52:55]
	v_mfma_f32_16x16x32_bf16 v[32:35], v[152:155], v[202:205], v[32:35]
	v_mfma_f32_16x16x32_bf16 v[32:35], v[156:159], v[206:209], v[32:35]
	v_mfma_f32_16x16x32_bf16 v[28:31], v[166:169], v[206:209], v[28:31]
	v_mfma_f32_16x16x32_bf16 v[28:31], v[162:165], v[202:205], v[28:31]
	v_mfma_f32_16x16x32_bf16 v[12:15], v[162:165], v[210:213], v[12:15]
	v_mfma_f32_16x16x32_bf16 v[12:15], v[166:169], v[214:217], v[12:15]
	v_mfma_f32_16x16x32_bf16 v[16:19], v[156:159], v[214:217], v[16:19]
	v_mfma_f32_16x16x32_bf16 v[16:19], v[152:155], v[210:213], v[16:19]
	v_mfma_f32_16x16x32_bf16 v[8:11], v[170:173], v[210:213], v[8:11]
	v_mfma_f32_16x16x32_bf16 v[8:11], v[174:177], v[214:217], v[8:11]
	v_mfma_f32_16x16x32_bf16 v[60:63], v[174:177], v[190:193], v[60:63]
	v_mfma_f32_16x16x32_bf16 v[60:63], v[170:173], v[186:189], v[60:63]
	v_mfma_f32_16x16x32_bf16 v[56:59], v[178:181], v[186:189], v[56:59]
	v_mfma_f32_16x16x32_bf16 v[56:59], v[182:185], v[190:193], v[56:59]
	v_mfma_f32_16x16x32_bf16 v[40:43], v[182:185], v[198:201], v[40:43]
	v_mfma_f32_16x16x32_bf16 v[40:43], v[178:181], v[194:197], v[40:43]
	v_mfma_f32_16x16x32_bf16 v[44:47], v[170:173], v[194:197], v[44:47]
	v_mfma_f32_16x16x32_bf16 v[44:47], v[174:177], v[198:201], v[44:47]
	v_mfma_f32_16x16x32_bf16 v[24:27], v[174:177], v[206:209], v[24:27]
	v_mfma_f32_16x16x32_bf16 v[24:27], v[170:173], v[202:205], v[24:27]
	v_mfma_f32_16x16x32_bf16 v[20:23], v[178:181], v[202:205], v[20:23]
	v_mfma_f32_16x16x32_bf16 v[20:23], v[182:185], v[206:209], v[20:23]
	v_mfma_f32_16x16x32_bf16 v[4:7], v[182:185], v[214:217], v[4:7]
	v_mfma_f32_16x16x32_bf16 v[4:7], v[178:181], v[210:213], v[4:7]
	s_setprio 0
	s_barrier
	s_add_i32 s13, 0, 0x18000
	v_add_u32_e32 v36, s13, v160
	s_add_i32 s68, 0, 0x1c000
	ds_read_b128 v[152:155], v36
	ds_read_b128 v[156:159], v36 offset:1024
	ds_read_b128 v[162:165], v36 offset:2048
	ds_read_b128 v[166:169], v36 offset:3072
	v_add_u32_e32 v36, s68, v160
	ds_read_b128 v[170:173], v36
	ds_read_b128 v[174:177], v36 offset:1024
	ds_read_b128 v[178:181], v36 offset:2048
	ds_read_b128 v[182:185], v36 offset:3072
	s_add_u32 s26, s26, 0x4000
	s_addc_u32 s27, s27, 0
	s_mov_b32 m0, s36
	ds_read_b128 v[186:189], v161 offset:32768
	ds_read_b128 v[190:193], v161 offset:33792
	ds_read_b128 v[194:197], v161 offset:34816
	ds_read_b128 v[198:201], v161 offset:35840
	ds_read_b128 v[202:205], v161 offset:36864
	ds_read_b128 v[206:209], v161 offset:37888
	ds_read_b128 v[210:213], v161 offset:38912
	ds_read_b128 v[214:217], v161 offset:39936
	global_load_lds_dwordx4 v142, s[26:27]
	s_mov_b32 m0, s37
	s_nop 0
	global_load_lds_dwordx4 v138, s[26:27]
	s_waitcnt vmcnt(8)
	s_waitcnt lgkmcnt(0)
	v_mfma_f32_16x16x32_bf16 v[132:135], v[152:155], v[186:189], v[132:135]
	v_mfma_f32_16x16x32_bf16 v[132:135], v[156:159], v[190:193], v[132:135]
	v_mfma_f32_16x16x32_bf16 v[128:131], v[166:169], v[190:193], v[128:131]
	v_mfma_f32_16x16x32_bf16 v[128:131], v[162:165], v[186:189], v[128:131]
	s_barrier
	s_setprio 1
	v_mfma_f32_16x16x32_bf16 v[112:115], v[162:165], v[194:197], v[112:115]
	v_mfma_f32_16x16x32_bf16 v[112:115], v[166:169], v[198:201], v[112:115]
	v_mfma_f32_16x16x32_bf16 v[116:119], v[156:159], v[198:201], v[116:119]
	v_mfma_f32_16x16x32_bf16 v[116:119], v[152:155], v[194:197], v[116:119]
	v_mfma_f32_16x16x32_bf16 v[100:103], v[152:155], v[202:205], v[100:103]
	v_mfma_f32_16x16x32_bf16 v[100:103], v[156:159], v[206:209], v[100:103]
	v_mfma_f32_16x16x32_bf16 v[96:99], v[166:169], v[206:209], v[96:99]
	v_mfma_f32_16x16x32_bf16 v[96:99], v[162:165], v[202:205], v[96:99]
	v_mfma_f32_16x16x32_bf16 v[80:83], v[162:165], v[210:213], v[80:83]
	v_mfma_f32_16x16x32_bf16 v[80:83], v[166:169], v[214:217], v[80:83]
	v_mfma_f32_16x16x32_bf16 v[84:87], v[156:159], v[214:217], v[84:87]
	v_mfma_f32_16x16x32_bf16 v[84:87], v[152:155], v[210:213], v[84:87]
	v_mfma_f32_16x16x32_bf16 v[76:79], v[170:173], v[210:213], v[76:79]
	v_mfma_f32_16x16x32_bf16 v[76:79], v[174:177], v[214:217], v[76:79]
	v_mfma_f32_16x16x32_bf16 v[124:127], v[174:177], v[190:193], v[124:127]
	v_mfma_f32_16x16x32_bf16 v[124:127], v[170:173], v[186:189], v[124:127]
	v_mfma_f32_16x16x32_bf16 v[120:123], v[178:181], v[186:189], v[120:123]
	v_mfma_f32_16x16x32_bf16 v[120:123], v[182:185], v[190:193], v[120:123]
	v_mfma_f32_16x16x32_bf16 v[104:107], v[182:185], v[198:201], v[104:107]
	v_mfma_f32_16x16x32_bf16 v[104:107], v[178:181], v[194:197], v[104:107]
	v_mfma_f32_16x16x32_bf16 v[108:111], v[170:173], v[194:197], v[108:111]
	v_mfma_f32_16x16x32_bf16 v[108:111], v[174:177], v[198:201], v[108:111]
	v_mfma_f32_16x16x32_bf16 v[92:95], v[174:177], v[206:209], v[92:95]
	v_mfma_f32_16x16x32_bf16 v[92:95], v[170:173], v[202:205], v[92:95]
	v_mfma_f32_16x16x32_bf16 v[88:91], v[178:181], v[202:205], v[88:91]
	v_mfma_f32_16x16x32_bf16 v[88:91], v[182:185], v[206:209], v[88:91]
	v_mfma_f32_16x16x32_bf16 v[72:75], v[182:185], v[214:217], v[72:75]
	v_mfma_f32_16x16x32_bf16 v[72:75], v[178:181], v[210:213], v[72:75]
	s_setprio 0
	s_barrier
; #define PG8_STAGE(bufoff, gbase, voff) do { _Pragma("unroll") for (int _i = 0; _i < 2; ++_i) \
;         __builtin_amdgcn_global_load_lds((const unsigned*)((const char*)(gbase) + (voff)[_i]), (PG8_LAS unsigned*)(lds + (bufoff) + ldsw + _i * 8192), 16, 0, 0); } while (0)
; #define PG8_LDA(dst, b, h) do { _Pragma("unroll") for (int m = 0; m < 4; ++m) _Pragma("unroll") for (int k = 0; k < 2; ++k) dst[m][k] = *(const PG8_LAS bf16x8*)(lds + PG8_SA(b, h) + aoff + m * 2048 + k * 1024); } while (0)
; #define PG8_MMA(ai, bj, At, Bt) do { __builtin_amdgcn_s_setprio(1); _Pragma("unroll") for (int m = 0; m < 4; ++m) _Pragma("unroll") for (int n = 0; n < 2; ++n) _Pragma("unroll") for (int k = 0; k < 2; ++k) \
;         acc[ai][bj][m][n] = __builtin_amdgcn_mfma_f32_16x16x32_bf16(Bt[n][k], At[m][k], acc[ai][bj][m][n], 0, 0, 0); __builtin_amdgcn_s_setprio(0); } while (0)
; #define PG8_WAIT_V(n) asm volatile("s_waitcnt vmcnt(" #n ")" ::: "memory")
; #define PG8_WAIT_L(n) asm volatile("s_waitcnt lgkmcnt(" #n ")" ::: "memory")
; #define PG8_BAR __builtin_amdgcn_s_barrier()
; #define PG8_SCHED __builtin_amdgcn_sched_barrier(0)
; template <class Epi, class Sched, bool ALIGN_EPI = false, bool SP2 = false, bool ABLK = false, bool BBLK = false>
; __device__ __forceinline__ void gemm_phase(PG8_LAS unsigned char* lds, const Gemm g, const Sched& S, const Epi& E) {
;     ...
;         for (int t = 0; t < nt; t += 2) {
;             const bool last = (t == nt - 2);
;     ...
;             PG8_LDA(At, 1, 1); PG8_STAGE(PG8_SB(1, 0), b3, voffB); PG8_STAGE(PG8_SB(1, 1), b3 + hstepB, voffB); PG8_STAGE(PG8_SA(1, 0), a3, voffA);
;             PG8_WAIT_V(8); PG8_WAIT_L(0); PG8_BAR; PG8_MMA(1, 0, At, B0); PG8_MMA(1, 1, At, B1); PG8_BAR; PG8_SCHED;
	s_add_u32 s26, s24, 0x8000
	s_addc_u32 s27, s25, 0
	s_add_i32 s13, s13, s31
	s_mov_b32 m0, s13
	ds_read_b128 v[186:189], v161 offset:49152
	ds_read_b128 v[190:193], v161 offset:50176
	ds_read_b128 v[194:197], v161 offset:51200
	ds_read_b128 v[198:201], v161 offset:52224
	ds_read_b128 v[202:205], v161 offset:53248
	ds_read_b128 v[206:209], v161 offset:54272
	ds_read_b128 v[210:213], v161 offset:55296
	ds_read_b128 v[214:217], v161 offset:56320
	global_load_lds_dwordx4 v140, s[26:27]
	s_add_i32 m0, s13, 0x2000
	s_add_u32 s24, s24, 0xc000
	s_addc_u32 s25, s25, 0
	s_add_i32 s13, s68, s31
	global_load_lds_dwordx4 v136, s[26:27]
	s_mov_b32 m0, s13
	s_nop 0
	global_load_lds_dwordx4 v140, s[24:25]
	s_add_i32 m0, s13, 0x2000
	s_nop 0
	global_load_lds_dwordx4 v136, s[24:25]
	s_mov_b32 m0, s62
	s_nop 0
	global_load_lds_dwordx4 v142, s[22:23]
	s_mov_b32 m0, s63
	s_nop 0
	global_load_lds_dwordx4 v138, s[22:23]
	s_waitcnt vmcnt(8)
	s_waitcnt lgkmcnt(0)
	v_mfma_f32_16x16x32_bf16 v[68:71], v[152:155], v[186:189], v[68:71]
	v_mfma_f32_16x16x32_bf16 v[68:71], v[156:159], v[190:193], v[68:71]
	v_mfma_f32_16x16x32_bf16 v[64:67], v[166:169], v[190:193], v[64:67]
	v_mfma_f32_16x16x32_bf16 v[64:67], v[162:165], v[186:189], v[64:67]
	s_barrier
	s_setprio 1
	v_mfma_f32_16x16x32_bf16 v[48:51], v[162:165], v[194:197], v[48:51]
	v_mfma_f32_16x16x32_bf16 v[48:51], v[166:169], v[198:201], v[48:51]
	v_mfma_f32_16x16x32_bf16 v[52:55], v[156:159], v[198:201], v[52:55]
	v_mfma_f32_16x16x32_bf16 v[52:55], v[152:155], v[194:197], v[52:55]
	v_mfma_f32_16x16x32_bf16 v[32:35], v[152:155], v[202:205], v[32:35]
	v_mfma_f32_16x16x32_bf16 v[32:35], v[156:159], v[206:209], v[32:35]
	v_mfma_f32_16x16x32_bf16 v[28:31], v[166:169], v[206:209], v[28:31]
	v_mfma_f32_16x16x32_bf16 v[28:31], v[162:165], v[202:205], v[28:31]
	v_mfma_f32_16x16x32_bf16 v[12:15], v[162:165], v[210:213], v[12:15]
	v_mfma_f32_16x16x32_bf16 v[12:15], v[166:169], v[214:217], v[12:15]
	v_mfma_f32_16x16x32_bf16 v[16:19], v[156:159], v[214:217], v[16:19]
	v_mfma_f32_16x16x32_bf16 v[16:19], v[152:155], v[210:213], v[16:19]
	v_mfma_f32_16x16x32_bf16 v[8:11], v[170:173], v[210:213], v[8:11]
	v_mfma_f32_16x16x32_bf16 v[8:11], v[174:177], v[214:217], v[8:11]
	v_mfma_f32_16x16x32_bf16 v[60:63], v[174:177], v[190:193], v[60:63]
	v_mfma_f32_16x16x32_bf16 v[60:63], v[170:173], v[186:189], v[60:63]
	v_mfma_f32_16x16x32_bf16 v[56:59], v[178:181], v[186:189], v[56:59]
	v_mfma_f32_16x16x32_bf16 v[56:59], v[182:185], v[190:193], v[56:59]
	v_mfma_f32_16x16x32_bf16 v[40:43], v[182:185], v[198:201], v[40:43]
	v_mfma_f32_16x16x32_bf16 v[40:43], v[178:181], v[194:197], v[40:43]
	v_mfma_f32_16x16x32_bf16 v[44:47], v[170:173], v[194:197], v[44:47]
	v_mfma_f32_16x16x32_bf16 v[44:47], v[174:177], v[198:201], v[44:47]
	v_mfma_f32_16x16x32_bf16 v[24:27], v[174:177], v[206:209], v[24:27]
	v_mfma_f32_16x16x32_bf16 v[24:27], v[170:173], v[202:205], v[24:27]
	v_mfma_f32_16x16x32_bf16 v[20:23], v[178:181], v[202:205], v[20:23]
	v_mfma_f32_16x16x32_bf16 v[20:23], v[182:185], v[206:209], v[20:23]
	v_mfma_f32_16x16x32_bf16 v[4:7], v[182:185], v[214:217], v[4:7]
	v_mfma_f32_16x16x32_bf16 v[4:7], v[178:181], v[210:213], v[4:7]
	s_setprio 0
	s_barrier
	s_add_i32 vcc_hi, vcc_hi, 2
	s_add_u32 s20, s20, 0x10000
	s_addc_u32 s21, s21, 0
	s_add_u32 s77, s77, 0x10000
	s_addc_u32 vcc_lo, vcc_lo, 0
	s_cmp_gt_u32 vcc_hi, 29
	s_cbranch_scc0 .LBB0_185
	s_and_b64 vcc, exec, s[4:5]
	s_cbranch_vccz .LBB0_188
	s_barrier

; #define PG8_STAGE(bufoff, gbase, voff) do { _Pragma("unroll") for (int _i = 0; _i < 2; ++_i) \
;         __builtin_amdgcn_global_load_lds((const unsigned*)((const char*)(gbase) + (voff)[_i]), (PG8_LAS unsigned*)(lds + (bufoff) + ldsw + _i * 8192), 16, 0, 0); } while (0)
; #define PG8_LDA(dst, b, h) do { _Pragma("unroll") for (int m = 0; m < 4; ++m) _Pragma("unroll") for (int k = 0; k < 2; ++k) dst[m][k] = *(const PG8_LAS bf16x8*)(lds + PG8_SA(b, h) + aoff + m * 2048 + k * 1024); } while (0)
; #define PG8_LDB(dst, b, h) do { _Pragma("unroll") for (int n = 0; n < 2; ++n) _Pragma("unroll") for (int k = 0; k < 2; ++k) dst[n][k] = *(const PG8_LAS bf16x8*)(lds + PG8_SB(b, h) + boff + n * 2048 + k * 1024); } while (0)
; #define PG8_MMA(ai, bj, At, Bt) do { __builtin_amdgcn_s_setprio(1); _Pragma("unroll") for (int m = 0; m < 4; ++m) _Pragma("unroll") for (int n = 0; n < 2; ++n) _Pragma("unroll") for (int k = 0; k < 2; ++k) \
;         acc[ai][bj][m][n] = __builtin_amdgcn_mfma_f32_16x16x32_bf16(Bt[n][k], At[m][k], acc[ai][bj][m][n], 0, 0, 0); __builtin_amdgcn_s_setprio(0); } while (0)
; #define PG8_WAIT_V(n) asm volatile("s_waitcnt vmcnt(" #n ")" ::: "memory")
; #define PG8_BAR __builtin_amdgcn_s_barrier()
; template <class Epi, class Sched, bool ALIGN_EPI = false, bool SP2 = false, bool ABLK = false, bool BBLK = false>
; __device__ __forceinline__ void gemm_phase(PG8_LAS unsigned char* lds, const Gemm g, const Sched& S, const Epi& E) {
;     ...
;             const bool last = (t == nt - 2);
;             const char* a1 = cA + (size_t)(t + 1) * kstepA;
;             const char* a2 = last ? nA : cA + (size_t)(t + 2) * kstepA; const char* b2 = last ? nB : cB + (size_t)(t + 2) * kstepB;
;             const char* a3 = a2 + kstepA; const char* b3 = b2 + kstepB;
;             if (last && has_next) S.a_ready(nxt);
;             if constexpr (SP2) {
;             PG8_LDB(B0, 0, 0); PG8_LDB(B1, 0, 1); PG8_SCHED; PG8_LDA(At, 0, 0); PG8_STAGE(PG8_SA(1, 1), a1 + hstepA, voffA);
;             PG8_WAIT_V(8); PG8_WAIT_L(0); PG8_BAR; PG8_MMA(0, 0, At, B0); PG8_MMA(0, 1, At, B1); PG8_BAR; PG8_SCHED;
;             PG8_LDA(At, 0, 1); PG8_STAGE(PG8_SB(0, 0), b2, voffB); PG8_STAGE(PG8_SB(0, 1), b2 + hstepB, voffB); PG8_STAGE(PG8_SA(0, 0), a2, voffA);
;             PG8_WAIT_V(8); PG8_WAIT_L(0); PG8_BAR; PG8_MMA(1, 0, At, B0); PG8_MMA(1, 1, At, B1); PG8_BAR; PG8_SCHED;
.LBB0_439:
	s_add_u32 s16, s10, 0x4000
	s_addc_u32 s17, s11, 0
	s_cmpk_eq_i32 s13, 0x54
	s_cselect_b32 s20, s0, s16
	s_cselect_b32 s21, s1, s17
	s_cselect_b32 s18, s8, vcc_lo
	s_cselect_b32 s19, s9, vcc_hi
	s_add_u32 s16, s20, 0x8000
	s_addc_u32 s17, s21, 0
	s_add_i32 s68, 0, 0x10000
	v_add_u32_e32 v36, s68, v148
	s_add_i32 s88, 0, 0x14000
	ds_read_b128 v[152:155], v36
	ds_read_b128 v[156:159], v36 offset:1024
	ds_read_b128 v[160:163], v36 offset:2048
	ds_read_b128 v[164:167], v36 offset:3072
	v_add_u32_e32 v36, s88, v148
	ds_read_b128 v[168:171], v36
	ds_read_b128 v[172:175], v36 offset:1024
	ds_read_b128 v[176:179], v36 offset:2048
	ds_read_b128 v[180:183], v36 offset:3072
	s_add_i32 m0, s27, 0xc000
	ds_read_b128 v[184:187], v150
	ds_read_b128 v[188:191], v150 offset:1024
	ds_read_b128 v[192:195], v150 offset:2048
	ds_read_b128 v[196:199], v150 offset:3072
	ds_read_b128 v[200:203], v150 offset:4096
	ds_read_b128 v[204:207], v150 offset:5120
	ds_read_b128 v[208:211], v150 offset:6144
	ds_read_b128 v[212:215], v150 offset:7168
	global_load_lds_dwordx4 v144, s[10:11]
	s_add_i32 m0, s27, 0xe000
	s_nop 0
	global_load_lds_dwordx4 v146, s[10:11]
	s_waitcnt vmcnt(8)
	s_waitcnt lgkmcnt(0)
	v_mfma_f32_16x16x32_bf16 v[132:135], v[152:155], v[184:187], v[132:135]
	v_mfma_f32_16x16x32_bf16 v[132:135], v[156:159], v[188:191], v[132:135]
	v_mfma_f32_16x16x32_bf16 v[128:131], v[164:167], v[188:191], v[128:131]
	v_mfma_f32_16x16x32_bf16 v[128:131], v[160:163], v[184:187], v[128:131]
	s_barrier
	s_setprio 1
	v_mfma_f32_16x16x32_bf16 v[120:123], v[160:163], v[192:195], v[120:123]
	v_mfma_f32_16x16x32_bf16 v[120:123], v[164:167], v[196:199], v[120:123]
	v_mfma_f32_16x16x32_bf16 v[124:127], v[156:159], v[196:199], v[124:127]
	v_mfma_f32_16x16x32_bf16 v[124:127], v[152:155], v[192:195], v[124:127]
	v_mfma_f32_16x16x32_bf16 v[108:111], v[152:155], v[200:203], v[108:111]
	v_mfma_f32_16x16x32_bf16 v[108:111], v[156:159], v[204:207], v[108:111]
	v_mfma_f32_16x16x32_bf16 v[104:107], v[164:167], v[204:207], v[104:107]
	v_mfma_f32_16x16x32_bf16 v[104:107], v[160:163], v[200:203], v[104:107]
	v_mfma_f32_16x16x32_bf16 v[88:91], v[160:163], v[208:211], v[88:91]
	v_mfma_f32_16x16x32_bf16 v[88:91], v[164:167], v[212:215], v[88:91]
	v_mfma_f32_16x16x32_bf16 v[92:95], v[156:159], v[212:215], v[92:95]
	v_mfma_f32_16x16x32_bf16 v[92:95], v[152:155], v[208:211], v[92:95]
	v_mfma_f32_16x16x32_bf16 v[76:79], v[168:171], v[208:211], v[76:79]
	v_mfma_f32_16x16x32_bf16 v[76:79], v[172:175], v[212:215], v[76:79]
	v_mfma_f32_16x16x32_bf16 v[116:119], v[172:175], v[188:191], v[116:119]
	v_mfma_f32_16x16x32_bf16 v[116:119], v[168:171], v[184:187], v[116:119]
	v_mfma_f32_16x16x32_bf16 v[112:115], v[176:179], v[184:187], v[112:115]
	v_mfma_f32_16x16x32_bf16 v[112:115], v[180:183], v[188:191], v[112:115]
	v_mfma_f32_16x16x32_bf16 v[96:99], v[180:183], v[196:199], v[96:99]
	v_mfma_f32_16x16x32_bf16 v[96:99], v[176:179], v[192:195], v[96:99]
	v_mfma_f32_16x16x32_bf16 v[100:103], v[168:171], v[192:195], v[100:103]
	v_mfma_f32_16x16x32_bf16 v[100:103], v[172:175], v[196:199], v[100:103]
	v_mfma_f32_16x16x32_bf16 v[84:87], v[172:175], v[204:207], v[84:87]
	v_mfma_f32_16x16x32_bf16 v[84:87], v[168:171], v[200:203], v[84:87]
	v_mfma_f32_16x16x32_bf16 v[80:83], v[176:179], v[200:203], v[80:83]
	v_mfma_f32_16x16x32_bf16 v[80:83], v[180:183], v[204:207], v[80:83]
	v_mfma_f32_16x16x32_bf16 v[72:75], v[180:183], v[212:215], v[72:75]
	v_mfma_f32_16x16x32_bf16 v[72:75], v[176:179], v[208:211], v[72:75]
	s_setprio 0
	s_barrier
	s_add_i32 s68, s68, s24
	s_mov_b32 m0, s68
	ds_read_b128 v[184:187], v150 offset:16384
	ds_read_b128 v[188:191], v150 offset:17408
	ds_read_b128 v[192:195], v150 offset:18432
	ds_read_b128 v[196:199], v150 offset:19456
	ds_read_b128 v[200:203], v150 offset:20480
	ds_read_b128 v[204:207], v150 offset:21504
	ds_read_b128 v[208:211], v150 offset:22528
	ds_read_b128 v[212:215], v150 offset:23552
	global_load_lds_dwordx4 v138, s[18:19]
	s_add_i32 m0, s68, 0x2000
	s_add_u32 s68, s18, 0x4000
	s_addc_u32 s69, s19, 0
	s_add_i32 s88, s88, s24
	global_load_lds_dwordx4 v142, s[18:19]
	s_mov_b32 m0, s88
	s_nop 0
	global_load_lds_dwordx4 v138, s[68:69]
	s_add_i32 m0, s88, 0x2000
	s_nop 0
	global_load_lds_dwordx4 v142, s[68:69]
	s_mov_b32 m0, s27
	s_nop 0
	global_load_lds_dwordx4 v136, s[20:21]
	s_mov_b32 m0, s28
	s_nop 0
	global_load_lds_dwordx4 v140, s[20:21]
	s_waitcnt vmcnt(8)
	s_waitcnt lgkmcnt(0)
	v_mfma_f32_16x16x32_bf16 v[68:71], v[152:155], v[184:187], v[68:71]
	v_mfma_f32_16x16x32_bf16 v[68:71], v[156:159], v[188:191], v[68:71]
	v_mfma_f32_16x16x32_bf16 v[64:67], v[164:167], v[188:191], v[64:67]
	v_mfma_f32_16x16x32_bf16 v[64:67], v[160:163], v[184:187], v[64:67]
	s_barrier
; #define PG8_STAGE(bufoff, gbase, voff) do { _Pragma("unroll") for (int _i = 0; _i < 2; ++_i) \
;         __builtin_amdgcn_global_load_lds((const unsigned*)((const char*)(gbase) + (voff)[_i]), (PG8_LAS unsigned*)(lds + (bufoff) + ldsw + _i * 8192), 16, 0, 0); } while (0)
; #define PG8_LDA(dst, b, h) do { _Pragma("unroll") for (int m = 0; m < 4; ++m) _Pragma("unroll") for (int k = 0; k < 2; ++k) dst[m][k] = *(const PG8_LAS bf16x8*)(lds + PG8_SA(b, h) + aoff + m * 2048 + k * 1024); } while (0)
; #define PG8_LDB(dst, b, h) do { _Pragma("unroll") for (int n = 0; n < 2; ++n) _Pragma("unroll") for (int k = 0; k < 2; ++k) dst[n][k] = *(const PG8_LAS bf16x8*)(lds + PG8_SB(b, h) + boff + n * 2048 + k * 1024); } while (0)
; #define PG8_MMA(ai, bj, At, Bt) do { __builtin_amdgcn_s_setprio(1); _Pragma("unroll") for (int m = 0; m < 4; ++m) _Pragma("unroll") for (int n = 0; n < 2; ++n) _Pragma("unroll") for (int k = 0; k < 2; ++k) \
;         acc[ai][bj][m][n] = __builtin_amdgcn_mfma_f32_16x16x32_bf16(Bt[n][k], At[m][k], acc[ai][bj][m][n], 0, 0, 0); __builtin_amdgcn_s_setprio(0); } while (0)
; #define PG8_WAIT_V(n) asm volatile("s_waitcnt vmcnt(" #n ")" ::: "memory")
; #define PG8_WAIT_L(n) asm volatile("s_waitcnt lgkmcnt(" #n ")" ::: "memory")
; #define PG8_BAR __builtin_amdgcn_s_barrier()
; #define PG8_SCHED __builtin_amdgcn_sched_barrier(0)
; template <class Epi, class Sched, bool ALIGN_EPI = false, bool SP2 = false, bool ABLK = false, bool BBLK = false>
; __device__ __forceinline__ void gemm_phase(PG8_LAS unsigned char* lds, const Gemm g, const Sched& S, const Epi& E) {
;     ...
;             PG8_WAIT_V(8); PG8_WAIT_L(0); PG8_BAR; PG8_MMA(1, 0, At, B0); PG8_MMA(1, 1, At, B1); PG8_BAR; PG8_SCHED;
;             PG8_LDB(B0, 1, 0); PG8_LDB(B1, 1, 1); PG8_SCHED; PG8_LDA(At, 1, 0); PG8_STAGE(PG8_SA(0, 1), a2 + hstepA, voffA);
;             PG8_WAIT_V(8); PG8_WAIT_L(0); PG8_BAR; PG8_MMA(0, 0, At, B0); PG8_MMA(0, 1, At, B1); PG8_BAR; PG8_SCHED;
	s_setprio 1
	v_mfma_f32_16x16x32_bf16 v[56:59], v[160:163], v[192:195], v[56:59]
	v_mfma_f32_16x16x32_bf16 v[56:59], v[164:167], v[196:199], v[56:59]
	v_mfma_f32_16x16x32_bf16 v[60:63], v[156:159], v[196:199], v[60:63]
	v_mfma_f32_16x16x32_bf16 v[60:63], v[152:155], v[192:195], v[60:63]
	v_mfma_f32_16x16x32_bf16 v[44:47], v[152:155], v[200:203], v[44:47]
	v_mfma_f32_16x16x32_bf16 v[44:47], v[156:159], v[204:207], v[44:47]
	v_mfma_f32_16x16x32_bf16 v[40:43], v[164:167], v[204:207], v[40:43]
	v_mfma_f32_16x16x32_bf16 v[40:43], v[160:163], v[200:203], v[40:43]
	v_mfma_f32_16x16x32_bf16 v[20:23], v[160:163], v[208:211], v[20:23]
	v_mfma_f32_16x16x32_bf16 v[20:23], v[164:167], v[212:215], v[20:23]
	v_mfma_f32_16x16x32_bf16 v[24:27], v[156:159], v[212:215], v[24:27]
	v_mfma_f32_16x16x32_bf16 v[24:27], v[152:155], v[208:211], v[24:27]
	v_mfma_f32_16x16x32_bf16 v[8:11], v[168:171], v[208:211], v[8:11]
	v_mfma_f32_16x16x32_bf16 v[8:11], v[172:175], v[212:215], v[8:11]
	v_mfma_f32_16x16x32_bf16 v[52:55], v[172:175], v[188:191], v[52:55]
	v_mfma_f32_16x16x32_bf16 v[52:55], v[168:171], v[184:187], v[52:55]
	v_mfma_f32_16x16x32_bf16 v[48:51], v[176:179], v[184:187], v[48:51]
	v_mfma_f32_16x16x32_bf16 v[48:51], v[180:183], v[188:191], v[48:51]
	v_mfma_f32_16x16x32_bf16 v[28:31], v[180:183], v[196:199], v[28:31]
	v_mfma_f32_16x16x32_bf16 v[28:31], v[176:179], v[192:195], v[28:31]
	v_mfma_f32_16x16x32_bf16 v[32:35], v[168:171], v[192:195], v[32:35]
	v_mfma_f32_16x16x32_bf16 v[32:35], v[172:175], v[196:199], v[32:35]
	v_mfma_f32_16x16x32_bf16 v[16:19], v[172:175], v[204:207], v[16:19]
	v_mfma_f32_16x16x32_bf16 v[16:19], v[168:171], v[200:203], v[16:19]
	v_mfma_f32_16x16x32_bf16 v[12:15], v[176:179], v[200:203], v[12:15]
	v_mfma_f32_16x16x32_bf16 v[12:15], v[180:183], v[204:207], v[12:15]
	v_mfma_f32_16x16x32_bf16 v[4:7], v[180:183], v[212:215], v[4:7]
	v_mfma_f32_16x16x32_bf16 v[4:7], v[176:179], v[208:211], v[4:7]
	s_setprio 0
	s_barrier
	s_add_i32 s68, 0, 0x18000
	v_add_u32_e32 v36, s68, v148
	s_add_i32 s69, 0, 0x1c000
	ds_read_b128 v[152:155], v36
	ds_read_b128 v[156:159], v36 offset:1024
	ds_read_b128 v[160:163], v36 offset:2048
	ds_read_b128 v[164:167], v36 offset:3072
	v_add_u32_e32 v36, s69, v148
	ds_read_b128 v[168:171], v36
	ds_read_b128 v[172:175], v36 offset:1024
	ds_read_b128 v[176:179], v36 offset:2048
	ds_read_b128 v[180:183], v36 offset:3072
	s_add_u32 s20, s20, 0x4000
	s_addc_u32 s21, s21, 0
	s_mov_b32 m0, s29
	ds_read_b128 v[184:187], v150 offset:32768
	ds_read_b128 v[188:191], v150 offset:33792
	ds_read_b128 v[192:195], v150 offset:34816
	ds_read_b128 v[196:199], v150 offset:35840
	ds_read_b128 v[200:203], v150 offset:36864
	ds_read_b128 v[204:207], v150 offset:37888
	ds_read_b128 v[208:211], v150 offset:38912
	ds_read_b128 v[212:215], v150 offset:39936
	global_load_lds_dwordx4 v136, s[20:21]
	s_mov_b32 m0, s30
	s_nop 0
	global_load_lds_dwordx4 v140, s[20:21]
	s_waitcnt vmcnt(8)
	s_waitcnt lgkmcnt(0)
	v_mfma_f32_16x16x32_bf16 v[132:135], v[152:155], v[184:187], v[132:135]
	v_mfma_f32_16x16x32_bf16 v[132:135], v[156:159], v[188:191], v[132:135]
	v_mfma_f32_16x16x32_bf16 v[128:131], v[164:167], v[188:191], v[128:131]
	v_mfma_f32_16x16x32_bf16 v[128:131], v[160:163], v[184:187], v[128:131]
	s_barrier
	s_setprio 1
	v_mfma_f32_16x16x32_bf16 v[120:123], v[160:163], v[192:195], v[120:123]
	v_mfma_f32_16x16x32_bf16 v[120:123], v[164:167], v[196:199], v[120:123]
	v_mfma_f32_16x16x32_bf16 v[124:127], v[156:159], v[196:199], v[124:127]
	v_mfma_f32_16x16x32_bf16 v[124:127], v[152:155], v[192:195], v[124:127]
	v_mfma_f32_16x16x32_bf16 v[108:111], v[152:155], v[200:203], v[108:111]
	v_mfma_f32_16x16x32_bf16 v[108:111], v[156:159], v[204:207], v[108:111]
	v_mfma_f32_16x16x32_bf16 v[104:107], v[164:167], v[204:207], v[104:107]
	v_mfma_f32_16x16x32_bf16 v[104:107], v[160:163], v[200:203], v[104:107]
	v_mfma_f32_16x16x32_bf16 v[88:91], v[160:163], v[208:211], v[88:91]
	v_mfma_f32_16x16x32_bf16 v[88:91], v[164:167], v[212:215], v[88:91]
	v_mfma_f32_16x16x32_bf16 v[92:95], v[156:159], v[212:215], v[92:95]
	v_mfma_f32_16x16x32_bf16 v[92:95], v[152:155], v[208:211], v[92:95]
	v_mfma_f32_16x16x32_bf16 v[76:79], v[168:171], v[208:211], v[76:79]
	v_mfma_f32_16x16x32_bf16 v[76:79], v[172:175], v[212:215], v[76:79]
	v_mfma_f32_16x16x32_bf16 v[116:119], v[172:175], v[188:191], v[116:119]
	v_mfma_f32_16x16x32_bf16 v[116:119], v[168:171], v[184:187], v[116:119]
	v_mfma_f32_16x16x32_bf16 v[112:115], v[176:179], v[184:187], v[112:115]
	v_mfma_f32_16x16x32_bf16 v[112:115], v[180:183], v[188:191], v[112:115]
	v_mfma_f32_16x16x32_bf16 v[96:99], v[180:183], v[196:199], v[96:99]
	v_mfma_f32_16x16x32_bf16 v[96:99], v[176:179], v[192:195], v[96:99]
	v_mfma_f32_16x16x32_bf16 v[100:103], v[168:171], v[192:195], v[100:103]
	v_mfma_f32_16x16x32_bf16 v[100:103], v[172:175], v[196:199], v[100:103]
	v_mfma_f32_16x16x32_bf16 v[84:87], v[172:175], v[204:207], v[84:87]
	v_mfma_f32_16x16x32_bf16 v[84:87], v[168:171], v[200:203], v[84:87]
	v_mfma_f32_16x16x32_bf16 v[80:83], v[176:179], v[200:203], v[80:83]
	v_mfma_f32_16x16x32_bf16 v[80:83], v[180:183], v[204:207], v[80:83]
	v_mfma_f32_16x16x32_bf16 v[72:75], v[180:183], v[212:215], v[72:75]
	v_mfma_f32_16x16x32_bf16 v[72:75], v[176:179], v[208:211], v[72:75]
	s_setprio 0
	s_barrier
; #define PG8_STAGE(bufoff, gbase, voff) do { _Pragma("unroll") for (int _i = 0; _i < 2; ++_i) \
;         __builtin_amdgcn_global_load_lds((const unsigned*)((const char*)(gbase) + (voff)[_i]), (PG8_LAS unsigned*)(lds + (bufoff) + ldsw + _i * 8192), 16, 0, 0); } while (0)
; #define PG8_LDA(dst, b, h) do { _Pragma("unroll") for (int m = 0; m < 4; ++m) _Pragma("unroll") for (int k = 0; k < 2; ++k) dst[m][k] = *(const PG8_LAS bf16x8*)(lds + PG8_SA(b, h) + aoff + m * 2048 + k * 1024); } while (0)
; #define PG8_MMA(ai, bj, At, Bt) do { __builtin_amdgcn_s_setprio(1); _Pragma("unroll") for (int m = 0; m < 4; ++m) _Pragma("unroll") for (int n = 0; n < 2; ++n) _Pragma("unroll") for (int k = 0; k < 2; ++k) \
;         acc[ai][bj][m][n] = __builtin_amdgcn_mfma_f32_16x16x32_bf16(Bt[n][k], At[m][k], acc[ai][bj][m][n], 0, 0, 0); __builtin_amdgcn_s_setprio(0); } while (0)
; #define PG8_WAIT_V(n) asm volatile("s_waitcnt vmcnt(" #n ")" ::: "memory")
; #define PG8_WAIT_L(n) asm volatile("s_waitcnt lgkmcnt(" #n ")" ::: "memory")
; #define PG8_BAR __builtin_amdgcn_s_barrier()
; #define PG8_SCHED __builtin_amdgcn_sched_barrier(0)
; template <class Epi, class Sched, bool ALIGN_EPI = false, bool SP2 = false, bool ABLK = false, bool BBLK = false>
; __device__ __forceinline__ void gemm_phase(PG8_LAS unsigned char* lds, const Gemm g, const Sched& S, const Epi& E) {
;     ...
;             PG8_LDA(At, 1, 1); PG8_STAGE(PG8_SB(1, 0), b3, voffB); PG8_STAGE(PG8_SB(1, 1), b3 + hstepB, voffB); PG8_STAGE(PG8_SA(1, 0), a3, voffA);
;             PG8_WAIT_V(8); PG8_WAIT_L(0); PG8_BAR; PG8_MMA(1, 0, At, B0); PG8_MMA(1, 1, At, B1); PG8_BAR; PG8_SCHED;
	s_add_u32 s20, s18, 0x8000
	s_addc_u32 s21, s19, 0
	s_add_i32 s68, s68, s24
	s_mov_b32 m0, s68
	ds_read_b128 v[184:187], v150 offset:49152
	ds_read_b128 v[188:191], v150 offset:50176
	ds_read_b128 v[192:195], v150 offset:51200
	ds_read_b128 v[196:199], v150 offset:52224
	ds_read_b128 v[200:203], v150 offset:53248
	ds_read_b128 v[204:207], v150 offset:54272
	ds_read_b128 v[208:211], v150 offset:55296
	ds_read_b128 v[212:215], v150 offset:56320
	global_load_lds_dwordx4 v138, s[20:21]
	s_add_i32 m0, s68, 0x2000
	s_add_u32 s18, s18, 0xc000
	s_addc_u32 s19, s19, 0
	global_load_lds_dwordx4 v142, s[20:21]
	s_add_i32 s20, s69, s24
	s_mov_b32 m0, s20
	s_nop 0
	global_load_lds_dwordx4 v138, s[18:19]
	s_add_i32 m0, s20, 0x2000
	s_nop 0
	global_load_lds_dwordx4 v142, s[18:19]
	s_mov_b32 m0, s35
	s_nop 0
	global_load_lds_dwordx4 v136, s[16:17]
	s_mov_b32 m0, s70
	s_nop 0
	global_load_lds_dwordx4 v140, s[16:17]
	s_waitcnt vmcnt(8)
	s_waitcnt lgkmcnt(0)
	v_mfma_f32_16x16x32_bf16 v[68:71], v[152:155], v[184:187], v[68:71]
	v_mfma_f32_16x16x32_bf16 v[68:71], v[156:159], v[188:191], v[68:71]
	v_mfma_f32_16x16x32_bf16 v[64:67], v[164:167], v[188:191], v[64:67]
	v_mfma_f32_16x16x32_bf16 v[64:67], v[160:163], v[184:187], v[64:67]
	s_barrier
	s_setprio 1
	v_mfma_f32_16x16x32_bf16 v[56:59], v[160:163], v[192:195], v[56:59]
	v_mfma_f32_16x16x32_bf16 v[56:59], v[164:167], v[196:199], v[56:59]
	v_mfma_f32_16x16x32_bf16 v[60:63], v[156:159], v[196:199], v[60:63]
	v_mfma_f32_16x16x32_bf16 v[60:63], v[152:155], v[192:195], v[60:63]
	v_mfma_f32_16x16x32_bf16 v[44:47], v[152:155], v[200:203], v[44:47]
	v_mfma_f32_16x16x32_bf16 v[44:47], v[156:159], v[204:207], v[44:47]
	v_mfma_f32_16x16x32_bf16 v[40:43], v[164:167], v[204:207], v[40:43]
	v_mfma_f32_16x16x32_bf16 v[40:43], v[160:163], v[200:203], v[40:43]
	v_mfma_f32_16x16x32_bf16 v[20:23], v[160:163], v[208:211], v[20:23]
	v_mfma_f32_16x16x32_bf16 v[20:23], v[164:167], v[212:215], v[20:23]
	v_mfma_f32_16x16x32_bf16 v[24:27], v[156:159], v[212:215], v[24:27]
	v_mfma_f32_16x16x32_bf16 v[24:27], v[152:155], v[208:211], v[24:27]
	v_mfma_f32_16x16x32_bf16 v[8:11], v[168:171], v[208:211], v[8:11]
	v_mfma_f32_16x16x32_bf16 v[8:11], v[172:175], v[212:215], v[8:11]
	v_mfma_f32_16x16x32_bf16 v[52:55], v[172:175], v[188:191], v[52:55]
	v_mfma_f32_16x16x32_bf16 v[52:55], v[168:171], v[184:187], v[52:55]
	v_mfma_f32_16x16x32_bf16 v[48:51], v[176:179], v[184:187], v[48:51]
	v_mfma_f32_16x16x32_bf16 v[48:51], v[180:183], v[188:191], v[48:51]
	v_mfma_f32_16x16x32_bf16 v[28:31], v[180:183], v[196:199], v[28:31]
	v_mfma_f32_16x16x32_bf16 v[28:31], v[176:179], v[192:195], v[28:31]
	v_mfma_f32_16x16x32_bf16 v[32:35], v[168:171], v[192:195], v[32:35]
	v_mfma_f32_16x16x32_bf16 v[32:35], v[172:175], v[196:199], v[32:35]
	v_mfma_f32_16x16x32_bf16 v[16:19], v[172:175], v[204:207], v[16:19]
	v_mfma_f32_16x16x32_bf16 v[16:19], v[168:171], v[200:203], v[16:19]
	v_mfma_f32_16x16x32_bf16 v[12:15], v[176:179], v[200:203], v[12:15]
	v_mfma_f32_16x16x32_bf16 v[12:15], v[180:183], v[204:207], v[12:15]
	v_mfma_f32_16x16x32_bf16 v[4:7], v[180:183], v[212:215], v[4:7]
	v_mfma_f32_16x16x32_bf16 v[4:7], v[176:179], v[208:211], v[4:7]
	s_setprio 0
	s_barrier
	s_add_i32 s13, s13, 2
	s_add_u32 s10, s10, 0x10000
	s_addc_u32 s11, s11, 0
	s_add_u32 vcc_lo, vcc_lo, 0x10000
	s_addc_u32 vcc_hi, vcc_hi, 0
	s_cmpk_gt_u32 s13, 0x55
	s_cbranch_scc0 .LBB0_439
	s_and_b64 vcc, exec, s[6:7]
	s_cbranch_vccz .LBB0_442
	s_barrier

; #define PG8_STAGE(bufoff, gbase, voff) do { _Pragma("unroll") for (int _i = 0; _i < 2; ++_i) \
;         __builtin_amdgcn_global_load_lds((const unsigned*)((const char*)(gbase) + (voff)[_i]), (PG8_LAS unsigned*)(lds + (bufoff) + ldsw + _i * 8192), 16, 0, 0); } while (0)
; #define PG8_LDA(dst, b, h) do { _Pragma("unroll") for (int m = 0; m < 4; ++m) _Pragma("unroll") for (int k = 0; k < 2; ++k) dst[m][k] = *(const PG8_LAS bf16x8*)(lds + PG8_SA(b, h) + aoff + m * 2048 + k * 1024); } while (0)
; #define PG8_LDB(dst, b, h) do { _Pragma("unroll") for (int n = 0; n < 2; ++n) _Pragma("unroll") for (int k = 0; k < 2; ++k) dst[n][k] = *(const PG8_LAS bf16x8*)(lds + PG8_SB(b, h) + boff + n * 2048 + k * 1024); } while (0)
; #define PG8_MMA(ai, bj, At, Bt) do { __builtin_amdgcn_s_setprio(1); _Pragma("unroll") for (int m = 0; m < 4; ++m) _Pragma("unroll") for (int n = 0; n < 2; ++n) _Pragma("unroll") for (int k = 0; k < 2; ++k) \
;         acc[ai][bj][m][n] = __builtin_amdgcn_mfma_f32_16x16x32_bf16(Bt[n][k], At[m][k], acc[ai][bj][m][n], 0, 0, 0); __builtin_amdgcn_s_setprio(0); } while (0)
; #define PG8_WAIT_V(n) asm volatile("s_waitcnt vmcnt(" #n ")" ::: "memory")
; #define PG8_BAR __builtin_amdgcn_s_barrier()
; template <class Epi, class Sched, bool ALIGN_EPI = false, bool SP2 = false, bool ABLK = false, bool BBLK = false>
; __device__ __forceinline__ void gemm_phase(PG8_LAS unsigned char* lds, const Gemm g, const Sched& S, const Epi& E) {
;     ...
;             const bool last = (t == nt - 2);
;             const char* a1 = cA + (size_t)(t + 1) * kstepA;
;             const char* a2 = last ? nA : cA + (size_t)(t + 2) * kstepA; const char* b2 = last ? nB : cB + (size_t)(t + 2) * kstepB;
;             const char* a3 = a2 + kstepA; const char* b3 = b2 + kstepB;
;             if (last && has_next) S.a_ready(nxt);
;             if constexpr (SP2) {
;             PG8_LDB(B0, 0, 0); PG8_LDB(B1, 0, 1); PG8_SCHED; PG8_LDA(At, 0, 0); PG8_STAGE(PG8_SA(1, 1), a1 + hstepA, voffA);
;             PG8_WAIT_V(8); PG8_WAIT_L(0); PG8_BAR; PG8_MMA(0, 0, At, B0); PG8_MMA(0, 1, At, B1); PG8_BAR; PG8_SCHED;
;             PG8_LDA(At, 0, 1); PG8_STAGE(PG8_SB(0, 0), b2, voffB); PG8_STAGE(PG8_SB(0, 1), b2 + hstepB, voffB); PG8_STAGE(PG8_SA(0, 0), a2, voffA);
;             PG8_WAIT_V(8); PG8_WAIT_L(0); PG8_BAR; PG8_MMA(1, 0, At, B0); PG8_MMA(1, 1, At, B1); PG8_BAR; PG8_SCHED;
.LBB0_916:
	s_add_u32 s22, s20, 0x4000
	s_addc_u32 s23, s21, 0
	s_cmp_eq_u32 s13, 28
	s_cselect_b32 s26, s19, s22
	s_cselect_b32 s27, s1, s23
	s_cselect_b32 s24, s65, s70
	s_cselect_b32 s25, s9, s71
	s_add_u32 s22, s26, 0x8000
	s_addc_u32 s23, s27, 0
	s_add_i32 s68, 0, 0x10000
	v_add_u32_e32 v36, s68, v155
	s_add_i32 s77, 0, 0x14000
	ds_read_b128 v[150:153], v36
	ds_read_b128 v[158:161], v36 offset:1024
	ds_read_b128 v[162:165], v36 offset:2048
	ds_read_b128 v[166:169], v36 offset:3072
	v_add_u32_e32 v36, s77, v155
	ds_read_b128 v[170:173], v36
	ds_read_b128 v[174:177], v36 offset:1024
	ds_read_b128 v[178:181], v36 offset:2048
	ds_read_b128 v[182:185], v36 offset:3072
	s_add_i32 m0, s31, 0xc000
	ds_read_b128 v[186:189], v157
	ds_read_b128 v[190:193], v157 offset:1024
	ds_read_b128 v[194:197], v157 offset:2048
	ds_read_b128 v[198:201], v157 offset:3072
	ds_read_b128 v[202:205], v157 offset:4096
	ds_read_b128 v[206:209], v157 offset:5120
	ds_read_b128 v[210:213], v157 offset:6144
	ds_read_b128 v[214:217], v157 offset:7168
	global_load_lds_dwordx4 v146, s[20:21]
	s_add_i32 m0, s31, 0xe000
	s_nop 0
	global_load_lds_dwordx4 v148, s[20:21]
	s_waitcnt vmcnt(8)
	s_waitcnt lgkmcnt(0)
	v_mfma_f32_16x16x32_bf16 v[132:135], v[150:153], v[186:189], v[132:135]
	v_mfma_f32_16x16x32_bf16 v[132:135], v[158:161], v[190:193], v[132:135]
	v_mfma_f32_16x16x32_bf16 v[128:131], v[166:169], v[190:193], v[128:131]
	v_mfma_f32_16x16x32_bf16 v[128:131], v[162:165], v[186:189], v[128:131]
	s_barrier
	s_setprio 1
	v_mfma_f32_16x16x32_bf16 v[116:119], v[162:165], v[194:197], v[116:119]
	v_mfma_f32_16x16x32_bf16 v[116:119], v[166:169], v[198:201], v[116:119]
	v_mfma_f32_16x16x32_bf16 v[124:127], v[158:161], v[198:201], v[124:127]
	v_mfma_f32_16x16x32_bf16 v[124:127], v[150:153], v[194:197], v[124:127]
	v_mfma_f32_16x16x32_bf16 v[108:111], v[150:153], v[202:205], v[108:111]
	v_mfma_f32_16x16x32_bf16 v[108:111], v[158:161], v[206:209], v[108:111]
	v_mfma_f32_16x16x32_bf16 v[100:103], v[166:169], v[206:209], v[100:103]
	v_mfma_f32_16x16x32_bf16 v[100:103], v[162:165], v[202:205], v[100:103]
	v_mfma_f32_16x16x32_bf16 v[84:87], v[162:165], v[210:213], v[84:87]
	v_mfma_f32_16x16x32_bf16 v[84:87], v[166:169], v[214:217], v[84:87]
	v_mfma_f32_16x16x32_bf16 v[92:95], v[158:161], v[214:217], v[92:95]
	v_mfma_f32_16x16x32_bf16 v[92:95], v[150:153], v[210:213], v[92:95]
	v_mfma_f32_16x16x32_bf16 v[76:79], v[170:173], v[210:213], v[76:79]
	v_mfma_f32_16x16x32_bf16 v[76:79], v[174:177], v[214:217], v[76:79]
	v_mfma_f32_16x16x32_bf16 v[120:123], v[174:177], v[190:193], v[120:123]
	v_mfma_f32_16x16x32_bf16 v[120:123], v[170:173], v[186:189], v[120:123]
	v_mfma_f32_16x16x32_bf16 v[112:115], v[178:181], v[186:189], v[112:115]
	v_mfma_f32_16x16x32_bf16 v[112:115], v[182:185], v[190:193], v[112:115]
	v_mfma_f32_16x16x32_bf16 v[96:99], v[182:185], v[198:201], v[96:99]
	v_mfma_f32_16x16x32_bf16 v[96:99], v[178:181], v[194:197], v[96:99]
	v_mfma_f32_16x16x32_bf16 v[104:107], v[170:173], v[194:197], v[104:107]
	v_mfma_f32_16x16x32_bf16 v[104:107], v[174:177], v[198:201], v[104:107]
	v_mfma_f32_16x16x32_bf16 v[88:91], v[174:177], v[206:209], v[88:91]
	v_mfma_f32_16x16x32_bf16 v[88:91], v[170:173], v[202:205], v[88:91]
	v_mfma_f32_16x16x32_bf16 v[80:83], v[178:181], v[202:205], v[80:83]
	v_mfma_f32_16x16x32_bf16 v[80:83], v[182:185], v[206:209], v[80:83]
	v_mfma_f32_16x16x32_bf16 v[72:75], v[182:185], v[214:217], v[72:75]
	v_mfma_f32_16x16x32_bf16 v[72:75], v[178:181], v[210:213], v[72:75]
	s_setprio 0
	s_barrier
	s_add_i32 s68, s68, s29
	s_mov_b32 m0, s68
	ds_read_b128 v[186:189], v157 offset:16384
	ds_read_b128 v[190:193], v157 offset:17408
	ds_read_b128 v[194:197], v157 offset:18432
	ds_read_b128 v[198:201], v157 offset:19456
	ds_read_b128 v[202:205], v157 offset:20480
	ds_read_b128 v[206:209], v157 offset:21504
	ds_read_b128 v[210:213], v157 offset:22528
	ds_read_b128 v[214:217], v157 offset:23552
	global_load_lds_dwordx4 v140, s[24:25]
	s_add_i32 m0, s68, 0x2000
	s_add_u32 s68, s24, 0x4000
	s_addc_u32 s69, s25, 0
	s_add_i32 s77, s77, s29
	global_load_lds_dwordx4 v136, s[24:25]
	s_mov_b32 m0, s77
	s_nop 0
	global_load_lds_dwordx4 v140, s[68:69]
	s_add_i32 m0, s77, 0x2000
	s_nop 0
	global_load_lds_dwordx4 v136, s[68:69]
	s_mov_b32 m0, s31
	s_nop 0
	global_load_lds_dwordx4 v142, s[26:27]
	s_mov_b32 m0, s34
	s_nop 0
	global_load_lds_dwordx4 v138, s[26:27]
	s_waitcnt vmcnt(8)
	s_waitcnt lgkmcnt(0)
	v_mfma_f32_16x16x32_bf16 v[68:71], v[150:153], v[186:189], v[68:71]
	v_mfma_f32_16x16x32_bf16 v[68:71], v[158:161], v[190:193], v[68:71]
	v_mfma_f32_16x16x32_bf16 v[64:67], v[166:169], v[190:193], v[64:67]
	v_mfma_f32_16x16x32_bf16 v[64:67], v[162:165], v[186:189], v[64:67]
	s_barrier
; #define PG8_STAGE(bufoff, gbase, voff) do { _Pragma("unroll") for (int _i = 0; _i < 2; ++_i) \
;         __builtin_amdgcn_global_load_lds((const unsigned*)((const char*)(gbase) + (voff)[_i]), (PG8_LAS unsigned*)(lds + (bufoff) + ldsw + _i * 8192), 16, 0, 0); } while (0)
; #define PG8_LDA(dst, b, h) do { _Pragma("unroll") for (int m = 0; m < 4; ++m) _Pragma("unroll") for (int k = 0; k < 2; ++k) dst[m][k] = *(const PG8_LAS bf16x8*)(lds + PG8_SA(b, h) + aoff + m * 2048 + k * 1024); } while (0)
; #define PG8_LDB(dst, b, h) do { _Pragma("unroll") for (int n = 0; n < 2; ++n) _Pragma("unroll") for (int k = 0; k < 2; ++k) dst[n][k] = *(const PG8_LAS bf16x8*)(lds + PG8_SB(b, h) + boff + n * 2048 + k * 1024); } while (0)
; #define PG8_MMA(ai, bj, At, Bt) do { __builtin_amdgcn_s_setprio(1); _Pragma("unroll") for (int m = 0; m < 4; ++m) _Pragma("unroll") for (int n = 0; n < 2; ++n) _Pragma("unroll") for (int k = 0; k < 2; ++k) \
;         acc[ai][bj][m][n] = __builtin_amdgcn_mfma_f32_16x16x32_bf16(Bt[n][k], At[m][k], acc[ai][bj][m][n], 0, 0, 0); __builtin_amdgcn_s_setprio(0); } while (0)
; #define PG8_WAIT_V(n) asm volatile("s_waitcnt vmcnt(" #n ")" ::: "memory")
; #define PG8_WAIT_L(n) asm volatile("s_waitcnt lgkmcnt(" #n ")" ::: "memory")
; #define PG8_BAR __builtin_amdgcn_s_barrier()
; #define PG8_SCHED __builtin_amdgcn_sched_barrier(0)
; template <class Epi, class Sched, bool ALIGN_EPI = false, bool SP2 = false, bool ABLK = false, bool BBLK = false>
; __device__ __forceinline__ void gemm_phase(PG8_LAS unsigned char* lds, const Gemm g, const Sched& S, const Epi& E) {
;     ...
;             PG8_WAIT_V(8); PG8_WAIT_L(0); PG8_BAR; PG8_MMA(1, 0, At, B0); PG8_MMA(1, 1, At, B1); PG8_BAR; PG8_SCHED;
;             PG8_LDB(B0, 1, 0); PG8_LDB(B1, 1, 1); PG8_SCHED; PG8_LDA(At, 1, 0); PG8_STAGE(PG8_SA(0, 1), a2 + hstepA, voffA);
;             PG8_WAIT_V(8); PG8_WAIT_L(0); PG8_BAR; PG8_MMA(0, 0, At, B0); PG8_MMA(0, 1, At, B1); PG8_BAR; PG8_SCHED;
	s_setprio 1
	v_mfma_f32_16x16x32_bf16 v[52:55], v[162:165], v[194:197], v[52:55]
	v_mfma_f32_16x16x32_bf16 v[52:55], v[166:169], v[198:201], v[52:55]
	v_mfma_f32_16x16x32_bf16 v[60:63], v[158:161], v[198:201], v[60:63]
	v_mfma_f32_16x16x32_bf16 v[60:63], v[150:153], v[194:197], v[60:63]
	v_mfma_f32_16x16x32_bf16 v[44:47], v[150:153], v[202:205], v[44:47]
	v_mfma_f32_16x16x32_bf16 v[44:47], v[158:161], v[206:209], v[44:47]
	v_mfma_f32_16x16x32_bf16 v[32:35], v[166:169], v[206:209], v[32:35]
	v_mfma_f32_16x16x32_bf16 v[32:35], v[162:165], v[202:205], v[32:35]
	v_mfma_f32_16x16x32_bf16 v[16:19], v[162:165], v[210:213], v[16:19]
	v_mfma_f32_16x16x32_bf16 v[16:19], v[166:169], v[214:217], v[16:19]
	v_mfma_f32_16x16x32_bf16 v[24:27], v[158:161], v[214:217], v[24:27]
	v_mfma_f32_16x16x32_bf16 v[24:27], v[150:153], v[210:213], v[24:27]
	v_mfma_f32_16x16x32_bf16 v[8:11], v[170:173], v[210:213], v[8:11]
	v_mfma_f32_16x16x32_bf16 v[8:11], v[174:177], v[214:217], v[8:11]
	v_mfma_f32_16x16x32_bf16 v[56:59], v[174:177], v[190:193], v[56:59]
	v_mfma_f32_16x16x32_bf16 v[56:59], v[170:173], v[186:189], v[56:59]
	v_mfma_f32_16x16x32_bf16 v[48:51], v[178:181], v[186:189], v[48:51]
	v_mfma_f32_16x16x32_bf16 v[48:51], v[182:185], v[190:193], v[48:51]
	v_mfma_f32_16x16x32_bf16 v[28:31], v[182:185], v[198:201], v[28:31]
	v_mfma_f32_16x16x32_bf16 v[28:31], v[178:181], v[194:197], v[28:31]
	v_mfma_f32_16x16x32_bf16 v[40:43], v[170:173], v[194:197], v[40:43]
	v_mfma_f32_16x16x32_bf16 v[40:43], v[174:177], v[198:201], v[40:43]
	v_mfma_f32_16x16x32_bf16 v[20:23], v[174:177], v[206:209], v[20:23]
	v_mfma_f32_16x16x32_bf16 v[20:23], v[170:173], v[202:205], v[20:23]
	v_mfma_f32_16x16x32_bf16 v[12:15], v[178:181], v[202:205], v[12:15]
	v_mfma_f32_16x16x32_bf16 v[12:15], v[182:185], v[206:209], v[12:15]
	v_mfma_f32_16x16x32_bf16 v[4:7], v[182:185], v[214:217], v[4:7]
	v_mfma_f32_16x16x32_bf16 v[4:7], v[178:181], v[210:213], v[4:7]
	s_setprio 0
	s_barrier
	s_add_i32 s68, 0, 0x18000
	v_add_u32_e32 v36, s68, v155
	s_add_i32 s69, 0, 0x1c000
	ds_read_b128 v[150:153], v36
	ds_read_b128 v[158:161], v36 offset:1024
	ds_read_b128 v[162:165], v36 offset:2048
	ds_read_b128 v[166:169], v36 offset:3072
	v_add_u32_e32 v36, s69, v155
	ds_read_b128 v[170:173], v36
	ds_read_b128 v[174:177], v36 offset:1024
	ds_read_b128 v[178:181], v36 offset:2048
	ds_read_b128 v[182:185], v36 offset:3072
	s_add_u32 s26, s26, 0x4000
	s_addc_u32 s27, s27, 0
	s_mov_b32 m0, s35
	ds_read_b128 v[186:189], v157 offset:32768
	ds_read_b128 v[190:193], v157 offset:33792
	ds_read_b128 v[194:197], v157 offset:34816
	ds_read_b128 v[198:201], v157 offset:35840
	ds_read_b128 v[202:205], v157 offset:36864
	ds_read_b128 v[206:209], v157 offset:37888
	ds_read_b128 v[210:213], v157 offset:38912
	ds_read_b128 v[214:217], v157 offset:39936
	global_load_lds_dwordx4 v142, s[26:27]
	s_mov_b32 m0, s36
	s_nop 0
	global_load_lds_dwordx4 v138, s[26:27]
	s_waitcnt vmcnt(8)
	s_waitcnt lgkmcnt(0)
	v_mfma_f32_16x16x32_bf16 v[132:135], v[150:153], v[186:189], v[132:135]
	v_mfma_f32_16x16x32_bf16 v[132:135], v[158:161], v[190:193], v[132:135]
	v_mfma_f32_16x16x32_bf16 v[128:131], v[166:169], v[190:193], v[128:131]
	v_mfma_f32_16x16x32_bf16 v[128:131], v[162:165], v[186:189], v[128:131]
	s_barrier
	s_setprio 1
	v_mfma_f32_16x16x32_bf16 v[116:119], v[162:165], v[194:197], v[116:119]
	v_mfma_f32_16x16x32_bf16 v[116:119], v[166:169], v[198:201], v[116:119]
	v_mfma_f32_16x16x32_bf16 v[124:127], v[158:161], v[198:201], v[124:127]
	v_mfma_f32_16x16x32_bf16 v[124:127], v[150:153], v[194:197], v[124:127]
	v_mfma_f32_16x16x32_bf16 v[108:111], v[150:153], v[202:205], v[108:111]
	v_mfma_f32_16x16x32_bf16 v[108:111], v[158:161], v[206:209], v[108:111]
	v_mfma_f32_16x16x32_bf16 v[100:103], v[166:169], v[206:209], v[100:103]
	v_mfma_f32_16x16x32_bf16 v[100:103], v[162:165], v[202:205], v[100:103]
	v_mfma_f32_16x16x32_bf16 v[84:87], v[162:165], v[210:213], v[84:87]
	v_mfma_f32_16x16x32_bf16 v[84:87], v[166:169], v[214:217], v[84:87]
	v_mfma_f32_16x16x32_bf16 v[92:95], v[158:161], v[214:217], v[92:95]
	v_mfma_f32_16x16x32_bf16 v[92:95], v[150:153], v[210:213], v[92:95]
	v_mfma_f32_16x16x32_bf16 v[76:79], v[170:173], v[210:213], v[76:79]
	v_mfma_f32_16x16x32_bf16 v[76:79], v[174:177], v[214:217], v[76:79]
	v_mfma_f32_16x16x32_bf16 v[120:123], v[174:177], v[190:193], v[120:123]
	v_mfma_f32_16x16x32_bf16 v[120:123], v[170:173], v[186:189], v[120:123]
	v_mfma_f32_16x16x32_bf16 v[112:115], v[178:181], v[186:189], v[112:115]
	v_mfma_f32_16x16x32_bf16 v[112:115], v[182:185], v[190:193], v[112:115]
	v_mfma_f32_16x16x32_bf16 v[96:99], v[182:185], v[198:201], v[96:99]
	v_mfma_f32_16x16x32_bf16 v[96:99], v[178:181], v[194:197], v[96:99]
	v_mfma_f32_16x16x32_bf16 v[104:107], v[170:173], v[194:197], v[104:107]
	v_mfma_f32_16x16x32_bf16 v[104:107], v[174:177], v[198:201], v[104:107]
	v_mfma_f32_16x16x32_bf16 v[88:91], v[174:177], v[206:209], v[88:91]
	v_mfma_f32_16x16x32_bf16 v[88:91], v[170:173], v[202:205], v[88:91]
	v_mfma_f32_16x16x32_bf16 v[80:83], v[178:181], v[202:205], v[80:83]
	v_mfma_f32_16x16x32_bf16 v[80:83], v[182:185], v[206:209], v[80:83]
	v_mfma_f32_16x16x32_bf16 v[72:75], v[182:185], v[214:217], v[72:75]
	v_mfma_f32_16x16x32_bf16 v[72:75], v[178:181], v[210:213], v[72:75]
	s_setprio 0
	s_barrier
; #define PG8_STAGE(bufoff, gbase, voff) do { _Pragma("unroll") for (int _i = 0; _i < 2; ++_i) \
;         __builtin_amdgcn_global_load_lds((const unsigned*)((const char*)(gbase) + (voff)[_i]), (PG8_LAS unsigned*)(lds + (bufoff) + ldsw + _i * 8192), 16, 0, 0); } while (0)
; #define PG8_LDA(dst, b, h) do { _Pragma("unroll") for (int m = 0; m < 4; ++m) _Pragma("unroll") for (int k = 0; k < 2; ++k) dst[m][k] = *(const PG8_LAS bf16x8*)(lds + PG8_SA(b, h) + aoff + m * 2048 + k * 1024); } while (0)
; #define PG8_MMA(ai, bj, At, Bt) do { __builtin_amdgcn_s_setprio(1); _Pragma("unroll") for (int m = 0; m < 4; ++m) _Pragma("unroll") for (int n = 0; n < 2; ++n) _Pragma("unroll") for (int k = 0; k < 2; ++k) \
;         acc[ai][bj][m][n] = __builtin_amdgcn_mfma_f32_16x16x32_bf16(Bt[n][k], At[m][k], acc[ai][bj][m][n], 0, 0, 0); __builtin_amdgcn_s_setprio(0); } while (0)
; #define PG8_WAIT_V(n) asm volatile("s_waitcnt vmcnt(" #n ")" ::: "memory")
; #define PG8_WAIT_L(n) asm volatile("s_waitcnt lgkmcnt(" #n ")" ::: "memory")
; #define PG8_BAR __builtin_amdgcn_s_barrier()
; #define PG8_SCHED __builtin_amdgcn_sched_barrier(0)
; template <class Epi, class Sched, bool ALIGN_EPI = false, bool SP2 = false, bool ABLK = false, bool BBLK = false>
; __device__ __forceinline__ void gemm_phase(PG8_LAS unsigned char* lds, const Gemm g, const Sched& S, const Epi& E) {
;     ...
;             PG8_LDA(At, 1, 1); PG8_STAGE(PG8_SB(1, 0), b3, voffB); PG8_STAGE(PG8_SB(1, 1), b3 + hstepB, voffB); PG8_STAGE(PG8_SA(1, 0), a3, voffA);
;             PG8_WAIT_V(8); PG8_WAIT_L(0); PG8_BAR; PG8_MMA(1, 0, At, B0); PG8_MMA(1, 1, At, B1); PG8_BAR; PG8_SCHED;
	s_add_u32 s26, s24, 0x8000
	s_addc_u32 s27, s25, 0
	s_add_i32 s68, s68, s29
	s_mov_b32 m0, s68
	ds_read_b128 v[186:189], v157 offset:49152
	ds_read_b128 v[190:193], v157 offset:50176
	ds_read_b128 v[194:197], v157 offset:51200
	ds_read_b128 v[198:201], v157 offset:52224
	ds_read_b128 v[202:205], v157 offset:53248
	ds_read_b128 v[206:209], v157 offset:54272
	ds_read_b128 v[210:213], v157 offset:55296
	ds_read_b128 v[214:217], v157 offset:56320
	global_load_lds_dwordx4 v140, s[26:27]
	s_add_i32 m0, s68, 0x2000
	s_add_u32 s24, s24, 0xc000
	s_addc_u32 s25, s25, 0
	global_load_lds_dwordx4 v136, s[26:27]
	s_add_i32 s26, s69, s29
	s_mov_b32 m0, s26
	s_nop 0
	global_load_lds_dwordx4 v140, s[24:25]
	s_add_i32 m0, s26, 0x2000
	s_nop 0
	global_load_lds_dwordx4 v136, s[24:25]
	s_mov_b32 m0, s37
	s_nop 0
	global_load_lds_dwordx4 v142, s[22:23]
	s_mov_b32 m0, s62
	s_nop 0
	global_load_lds_dwordx4 v138, s[22:23]
	s_waitcnt vmcnt(8)
	s_waitcnt lgkmcnt(0)
	v_mfma_f32_16x16x32_bf16 v[68:71], v[150:153], v[186:189], v[68:71]
	v_mfma_f32_16x16x32_bf16 v[68:71], v[158:161], v[190:193], v[68:71]
	v_mfma_f32_16x16x32_bf16 v[64:67], v[166:169], v[190:193], v[64:67]
	v_mfma_f32_16x16x32_bf16 v[64:67], v[162:165], v[186:189], v[64:67]
	s_barrier
	s_setprio 1
	v_mfma_f32_16x16x32_bf16 v[52:55], v[162:165], v[194:197], v[52:55]
	v_mfma_f32_16x16x32_bf16 v[52:55], v[166:169], v[198:201], v[52:55]
	v_mfma_f32_16x16x32_bf16 v[60:63], v[158:161], v[198:201], v[60:63]
	v_mfma_f32_16x16x32_bf16 v[60:63], v[150:153], v[194:197], v[60:63]
	v_mfma_f32_16x16x32_bf16 v[44:47], v[150:153], v[202:205], v[44:47]
	v_mfma_f32_16x16x32_bf16 v[44:47], v[158:161], v[206:209], v[44:47]
	v_mfma_f32_16x16x32_bf16 v[32:35], v[166:169], v[206:209], v[32:35]
	v_mfma_f32_16x16x32_bf16 v[32:35], v[162:165], v[202:205], v[32:35]
	v_mfma_f32_16x16x32_bf16 v[16:19], v[162:165], v[210:213], v[16:19]
	v_mfma_f32_16x16x32_bf16 v[16:19], v[166:169], v[214:217], v[16:19]
	v_mfma_f32_16x16x32_bf16 v[24:27], v[158:161], v[214:217], v[24:27]
	v_mfma_f32_16x16x32_bf16 v[24:27], v[150:153], v[210:213], v[24:27]
	v_mfma_f32_16x16x32_bf16 v[8:11], v[170:173], v[210:213], v[8:11]
	v_mfma_f32_16x16x32_bf16 v[8:11], v[174:177], v[214:217], v[8:11]
	v_mfma_f32_16x16x32_bf16 v[56:59], v[174:177], v[190:193], v[56:59]
	v_mfma_f32_16x16x32_bf16 v[56:59], v[170:173], v[186:189], v[56:59]
	v_mfma_f32_16x16x32_bf16 v[48:51], v[178:181], v[186:189], v[48:51]
	v_mfma_f32_16x16x32_bf16 v[48:51], v[182:185], v[190:193], v[48:51]
	v_mfma_f32_16x16x32_bf16 v[28:31], v[182:185], v[198:201], v[28:31]
	v_mfma_f32_16x16x32_bf16 v[28:31], v[178:181], v[194:197], v[28:31]
	v_mfma_f32_16x16x32_bf16 v[40:43], v[170:173], v[194:197], v[40:43]
	v_mfma_f32_16x16x32_bf16 v[40:43], v[174:177], v[198:201], v[40:43]
	v_mfma_f32_16x16x32_bf16 v[20:23], v[174:177], v[206:209], v[20:23]
	v_mfma_f32_16x16x32_bf16 v[20:23], v[170:173], v[202:205], v[20:23]
	v_mfma_f32_16x16x32_bf16 v[12:15], v[178:181], v[202:205], v[12:15]
	v_mfma_f32_16x16x32_bf16 v[12:15], v[182:185], v[206:209], v[12:15]
	v_mfma_f32_16x16x32_bf16 v[4:7], v[182:185], v[214:217], v[4:7]
	v_mfma_f32_16x16x32_bf16 v[4:7], v[178:181], v[210:213], v[4:7]
	s_setprio 0
	s_barrier
	s_add_i32 s13, s13, 2
	s_add_u32 s20, s20, 0x10000
	s_addc_u32 s21, s21, 0
	s_add_u32 s70, s70, 0x10000
	s_addc_u32 s71, s71, 0
	s_cmp_gt_u32 s13, 29
	s_cbranch_scc0 .LBB0_916
	s_and_b64 vcc, exec, s[6:7]
	s_cbranch_vccz .LBB0_919
	s_barrier

; #define PG8_STAGE(bufoff, gbase, voff) do { _Pragma("unroll") for (int _i = 0; _i < 2; ++_i) \
;         __builtin_amdgcn_global_load_lds((const unsigned*)((const char*)(gbase) + (voff)[_i]), (PG8_LAS unsigned*)(lds + (bufoff) + ldsw + _i * 8192), 16, 0, 0); } while (0)
; #define PG8_LDA(dst, b, h) do { _Pragma("unroll") for (int m = 0; m < 4; ++m) _Pragma("unroll") for (int k = 0; k < 2; ++k) dst[m][k] = *(const PG8_LAS bf16x8*)(lds + PG8_SA(b, h) + aoff + m * 2048 + k * 1024); } while (0)
; #define PG8_LDB(dst, b, h) do { _Pragma("unroll") for (int n = 0; n < 2; ++n) _Pragma("unroll") for (int k = 0; k < 2; ++k) dst[n][k] = *(const PG8_LAS bf16x8*)(lds + PG8_SB(b, h) + boff + n * 2048 + k * 1024); } while (0)
; #define PG8_MMA(ai, bj, At, Bt) do { __builtin_amdgcn_s_setprio(1); _Pragma("unroll") for (int m = 0; m < 4; ++m) _Pragma("unroll") for (int n = 0; n < 2; ++n) _Pragma("unroll") for (int k = 0; k < 2; ++k) \
;         acc[ai][bj][m][n] = __builtin_amdgcn_mfma_f32_16x16x32_bf16(Bt[n][k], At[m][k], acc[ai][bj][m][n], 0, 0, 0); __builtin_amdgcn_s_setprio(0); } while (0)
; #define PG8_WAIT_V(n) asm volatile("s_waitcnt vmcnt(" #n ")" ::: "memory")
; #define PG8_BAR __builtin_amdgcn_s_barrier()
; template <class Epi, class Sched, bool ALIGN_EPI = false, bool SP2 = false, bool ABLK = false, bool BBLK = false>
; __device__ __forceinline__ void gemm_phase(PG8_LAS unsigned char* lds, const Gemm g, const Sched& S, const Epi& E) {
;     ...
;             const bool last = (t == nt - 2);
;             const char* a1 = cA + (size_t)(t + 1) * kstepA;
;             const char* a2 = last ? nA : cA + (size_t)(t + 2) * kstepA; const char* b2 = last ? nB : cB + (size_t)(t + 2) * kstepB;
;             const char* a3 = a2 + kstepA; const char* b3 = b2 + kstepB;
;             if (last && has_next) S.a_ready(nxt);
;             if constexpr (SP2) {
;             PG8_LDB(B0, 0, 0); PG8_LDB(B1, 0, 1); PG8_SCHED; PG8_LDA(At, 0, 0); PG8_STAGE(PG8_SA(1, 1), a1 + hstepA, voffA);
;             PG8_WAIT_V(8); PG8_WAIT_L(0); PG8_BAR; PG8_MMA(0, 0, At, B0); PG8_MMA(0, 1, At, B1); PG8_BAR; PG8_SCHED;
;             PG8_LDA(At, 0, 1); PG8_STAGE(PG8_SB(0, 0), b2, voffB); PG8_STAGE(PG8_SB(0, 1), b2 + hstepB, voffB); PG8_STAGE(PG8_SA(0, 0), a2, voffA);
;             PG8_WAIT_V(8); PG8_WAIT_L(0); PG8_BAR; PG8_MMA(1, 0, At, B0); PG8_MMA(1, 1, At, B1); PG8_BAR; PG8_SCHED;
.LBB0_2111:
	s_add_u32 s24, s22, 0x4000
	s_addc_u32 s25, s23, 0
	s_cmp_eq_u32 s13, 28
	s_cselect_b32 s28, s17, s24
	s_cselect_b32 s29, s12, s25
	s_cselect_b32 s26, s77, s82
	s_cselect_b32 s27, s11, vcc_lo
	s_add_u32 s24, s28, 0x8000
	s_addc_u32 s25, s29, 0
	s_add_i32 s68, 0, 0x10000
	v_add_u32_e32 v151, s68, v148
	s_add_i32 s88, 0, 0x14000
	ds_read_b128 v[36:39], v151
	ds_read_b128 v[152:155], v151 offset:1024
	ds_read_b128 v[156:159], v151 offset:2048
	ds_read_b128 v[160:163], v151 offset:3072
	v_add_u32_e32 v151, s88, v148
	ds_read_b128 v[164:167], v151
	ds_read_b128 v[168:171], v151 offset:1024
	ds_read_b128 v[172:175], v151 offset:2048
	ds_read_b128 v[176:179], v151 offset:3072
	s_add_i32 m0, s9, 0xc000
	ds_read_b128 v[180:183], v150
	ds_read_b128 v[184:187], v150 offset:1024
	ds_read_b128 v[188:191], v150 offset:2048
	ds_read_b128 v[192:195], v150 offset:3072
	ds_read_b128 v[196:199], v150 offset:4096
	ds_read_b128 v[200:203], v150 offset:5120
	ds_read_b128 v[204:207], v150 offset:6144
	ds_read_b128 v[208:211], v150 offset:7168
	global_load_lds_dwordx4 v144, s[22:23]
	s_add_i32 m0, s9, 0xe000
	s_nop 0
	global_load_lds_dwordx4 v146, s[22:23]
	s_waitcnt vmcnt(8)
	s_waitcnt lgkmcnt(0)
	v_mfma_f32_16x16x32_bf16 v[132:135], v[36:39], v[180:183], v[132:135]
	v_mfma_f32_16x16x32_bf16 v[132:135], v[152:155], v[184:187], v[132:135]
	v_mfma_f32_16x16x32_bf16 v[128:131], v[160:163], v[184:187], v[128:131]
	v_mfma_f32_16x16x32_bf16 v[128:131], v[156:159], v[180:183], v[128:131]
	s_barrier
	s_setprio 1
	v_mfma_f32_16x16x32_bf16 v[120:123], v[156:159], v[188:191], v[120:123]
	v_mfma_f32_16x16x32_bf16 v[120:123], v[160:163], v[192:195], v[120:123]
	v_mfma_f32_16x16x32_bf16 v[124:127], v[152:155], v[192:195], v[124:127]
	v_mfma_f32_16x16x32_bf16 v[124:127], v[36:39], v[188:191], v[124:127]
	v_mfma_f32_16x16x32_bf16 v[108:111], v[36:39], v[196:199], v[108:111]
	v_mfma_f32_16x16x32_bf16 v[108:111], v[152:155], v[200:203], v[108:111]
	v_mfma_f32_16x16x32_bf16 v[104:107], v[160:163], v[200:203], v[104:107]
	v_mfma_f32_16x16x32_bf16 v[104:107], v[156:159], v[196:199], v[104:107]
	v_mfma_f32_16x16x32_bf16 v[88:91], v[156:159], v[204:207], v[88:91]
	v_mfma_f32_16x16x32_bf16 v[88:91], v[160:163], v[208:211], v[88:91]
	v_mfma_f32_16x16x32_bf16 v[92:95], v[152:155], v[208:211], v[92:95]
	v_mfma_f32_16x16x32_bf16 v[92:95], v[36:39], v[204:207], v[92:95]
	v_mfma_f32_16x16x32_bf16 v[76:79], v[164:167], v[204:207], v[76:79]
	v_mfma_f32_16x16x32_bf16 v[76:79], v[168:171], v[208:211], v[76:79]
	v_mfma_f32_16x16x32_bf16 v[116:119], v[168:171], v[184:187], v[116:119]
	v_mfma_f32_16x16x32_bf16 v[116:119], v[164:167], v[180:183], v[116:119]
	v_mfma_f32_16x16x32_bf16 v[112:115], v[172:175], v[180:183], v[112:115]
	v_mfma_f32_16x16x32_bf16 v[112:115], v[176:179], v[184:187], v[112:115]
	v_mfma_f32_16x16x32_bf16 v[96:99], v[176:179], v[192:195], v[96:99]
	v_mfma_f32_16x16x32_bf16 v[96:99], v[172:175], v[188:191], v[96:99]
	v_mfma_f32_16x16x32_bf16 v[100:103], v[164:167], v[188:191], v[100:103]
	v_mfma_f32_16x16x32_bf16 v[100:103], v[168:171], v[192:195], v[100:103]
	v_mfma_f32_16x16x32_bf16 v[84:87], v[168:171], v[200:203], v[84:87]
	v_mfma_f32_16x16x32_bf16 v[84:87], v[164:167], v[196:199], v[84:87]
	v_mfma_f32_16x16x32_bf16 v[80:83], v[172:175], v[196:199], v[80:83]
	v_mfma_f32_16x16x32_bf16 v[80:83], v[176:179], v[200:203], v[80:83]
	v_mfma_f32_16x16x32_bf16 v[72:75], v[176:179], v[208:211], v[72:75]
	v_mfma_f32_16x16x32_bf16 v[72:75], v[172:175], v[204:207], v[72:75]
	s_setprio 0
	s_barrier
	s_add_i32 s68, s68, s34
	s_mov_b32 m0, s68
	ds_read_b128 v[180:183], v150 offset:16384
	ds_read_b128 v[184:187], v150 offset:17408
	ds_read_b128 v[188:191], v150 offset:18432
	ds_read_b128 v[192:195], v150 offset:19456
	ds_read_b128 v[196:199], v150 offset:20480
	ds_read_b128 v[200:203], v150 offset:21504
	ds_read_b128 v[204:207], v150 offset:22528
	ds_read_b128 v[208:211], v150 offset:23552
	global_load_lds_dwordx4 v138, s[26:27]
	s_add_i32 m0, s68, 0x2000
	s_add_u32 s68, s26, 0x4000
	s_addc_u32 s69, s27, 0
	s_add_i32 s88, s88, s34
	global_load_lds_dwordx4 v142, s[26:27]
	s_mov_b32 m0, s88
	s_nop 0
	global_load_lds_dwordx4 v138, s[68:69]
	s_add_i32 m0, s88, 0x2000
	s_nop 0
	global_load_lds_dwordx4 v142, s[68:69]
	s_mov_b32 m0, s9
	s_nop 0
	global_load_lds_dwordx4 v136, s[28:29]
	s_mov_b32 m0, s35
	s_nop 0
	global_load_lds_dwordx4 v140, s[28:29]
	s_waitcnt vmcnt(8)
	s_waitcnt lgkmcnt(0)
	v_mfma_f32_16x16x32_bf16 v[68:71], v[36:39], v[180:183], v[68:71]
	v_mfma_f32_16x16x32_bf16 v[68:71], v[152:155], v[184:187], v[68:71]
	v_mfma_f32_16x16x32_bf16 v[64:67], v[160:163], v[184:187], v[64:67]
	v_mfma_f32_16x16x32_bf16 v[64:67], v[156:159], v[180:183], v[64:67]
	s_barrier
; #define PG8_STAGE(bufoff, gbase, voff) do { _Pragma("unroll") for (int _i = 0; _i < 2; ++_i) \
;         __builtin_amdgcn_global_load_lds((const unsigned*)((const char*)(gbase) + (voff)[_i]), (PG8_LAS unsigned*)(lds + (bufoff) + ldsw + _i * 8192), 16, 0, 0); } while (0)
; #define PG8_LDA(dst, b, h) do { _Pragma("unroll") for (int m = 0; m < 4; ++m) _Pragma("unroll") for (int k = 0; k < 2; ++k) dst[m][k] = *(const PG8_LAS bf16x8*)(lds + PG8_SA(b, h) + aoff + m * 2048 + k * 1024); } while (0)
; #define PG8_LDB(dst, b, h) do { _Pragma("unroll") for (int n = 0; n < 2; ++n) _Pragma("unroll") for (int k = 0; k < 2; ++k) dst[n][k] = *(const PG8_LAS bf16x8*)(lds + PG8_SB(b, h) + boff + n * 2048 + k * 1024); } while (0)
; #define PG8_MMA(ai, bj, At, Bt) do { __builtin_amdgcn_s_setprio(1); _Pragma("unroll") for (int m = 0; m < 4; ++m) _Pragma("unroll") for (int n = 0; n < 2; ++n) _Pragma("unroll") for (int k = 0; k < 2; ++k) \
;         acc[ai][bj][m][n] = __builtin_amdgcn_mfma_f32_16x16x32_bf16(Bt[n][k], At[m][k], acc[ai][bj][m][n], 0, 0, 0); __builtin_amdgcn_s_setprio(0); } while (0)
; #define PG8_WAIT_V(n) asm volatile("s_waitcnt vmcnt(" #n ")" ::: "memory")
; #define PG8_WAIT_L(n) asm volatile("s_waitcnt lgkmcnt(" #n ")" ::: "memory")
; #define PG8_BAR __builtin_amdgcn_s_barrier()
; #define PG8_SCHED __builtin_amdgcn_sched_barrier(0)
; template <class Epi, class Sched, bool ALIGN_EPI = false, bool SP2 = false, bool ABLK = false, bool BBLK = false>
; __device__ __forceinline__ void gemm_phase(PG8_LAS unsigned char* lds, const Gemm g, const Sched& S, const Epi& E) {
;     ...
;             PG8_WAIT_V(8); PG8_WAIT_L(0); PG8_BAR; PG8_MMA(1, 0, At, B0); PG8_MMA(1, 1, At, B1); PG8_BAR; PG8_SCHED;
;             PG8_LDB(B0, 1, 0); PG8_LDB(B1, 1, 1); PG8_SCHED; PG8_LDA(At, 1, 0); PG8_STAGE(PG8_SA(0, 1), a2 + hstepA, voffA);
;             PG8_WAIT_V(8); PG8_WAIT_L(0); PG8_BAR; PG8_MMA(0, 0, At, B0); PG8_MMA(0, 1, At, B1); PG8_BAR; PG8_SCHED;
	s_setprio 1
	v_mfma_f32_16x16x32_bf16 v[56:59], v[156:159], v[188:191], v[56:59]
	v_mfma_f32_16x16x32_bf16 v[56:59], v[160:163], v[192:195], v[56:59]
	v_mfma_f32_16x16x32_bf16 v[60:63], v[152:155], v[192:195], v[60:63]
	v_mfma_f32_16x16x32_bf16 v[60:63], v[36:39], v[188:191], v[60:63]
	v_mfma_f32_16x16x32_bf16 v[44:47], v[36:39], v[196:199], v[44:47]
	v_mfma_f32_16x16x32_bf16 v[44:47], v[152:155], v[200:203], v[44:47]
	v_mfma_f32_16x16x32_bf16 v[40:43], v[160:163], v[200:203], v[40:43]
	v_mfma_f32_16x16x32_bf16 v[40:43], v[156:159], v[196:199], v[40:43]
	v_mfma_f32_16x16x32_bf16 v[20:23], v[156:159], v[204:207], v[20:23]
	v_mfma_f32_16x16x32_bf16 v[20:23], v[160:163], v[208:211], v[20:23]
	v_mfma_f32_16x16x32_bf16 v[24:27], v[152:155], v[208:211], v[24:27]
	v_mfma_f32_16x16x32_bf16 v[24:27], v[36:39], v[204:207], v[24:27]
	v_mfma_f32_16x16x32_bf16 v[48:51], v[172:175], v[180:183], v[48:51]
	v_mfma_f32_16x16x32_bf16 v[32:35], v[164:167], v[188:191], v[32:35]
	v_mfma_f32_16x16x32_bf16 v[28:31], v[172:175], v[188:191], v[28:31]
	v_mfma_f32_16x16x32_bf16 v[16:19], v[164:167], v[196:199], v[16:19]
	v_mfma_f32_16x16x32_bf16 v[12:15], v[172:175], v[196:199], v[12:15]
	v_mfma_f32_16x16x32_bf16 v[8:11], v[164:167], v[204:207], v[8:11]
	v_mfma_f32_16x16x32_bf16 v[4:7], v[172:175], v[204:207], v[4:7]
	v_mfma_f32_16x16x32_bf16 v[36:39], v[164:167], v[180:183], v[52:55]
	v_mfma_f32_16x16x32_bf16 v[48:51], v[176:179], v[184:187], v[48:51]
	v_mfma_f32_16x16x32_bf16 v[32:35], v[168:171], v[192:195], v[32:35]
	v_mfma_f32_16x16x32_bf16 v[28:31], v[176:179], v[192:195], v[28:31]
	v_mfma_f32_16x16x32_bf16 v[16:19], v[168:171], v[200:203], v[16:19]
	v_mfma_f32_16x16x32_bf16 v[12:15], v[176:179], v[200:203], v[12:15]
	v_mfma_f32_16x16x32_bf16 v[8:11], v[168:171], v[208:211], v[8:11]
	v_mfma_f32_16x16x32_bf16 v[4:7], v[176:179], v[208:211], v[4:7]
	v_mfma_f32_16x16x32_bf16 v[36:39], v[168:171], v[184:187], v[36:39]
	s_setprio 0
	s_barrier
	s_add_i32 s68, 0, 0x18000
	v_add_u32_e32 v151, s68, v148
	s_add_i32 s69, 0, 0x1c000
	ds_read_b128 v[52:55], v151
	ds_read_b128 v[152:155], v151 offset:1024
	ds_read_b128 v[156:159], v151 offset:2048
	ds_read_b128 v[160:163], v151 offset:3072
	v_add_u32_e32 v151, s69, v148
	ds_read_b128 v[164:167], v151
	ds_read_b128 v[168:171], v151 offset:1024
	ds_read_b128 v[172:175], v151 offset:2048
	ds_read_b128 v[176:179], v151 offset:3072
	s_add_u32 s28, s28, 0x4000
	s_addc_u32 s29, s29, 0
	s_mov_b32 m0, s36
	ds_read_b128 v[180:183], v150 offset:32768
	ds_read_b128 v[184:187], v150 offset:33792
	ds_read_b128 v[188:191], v150 offset:34816
	ds_read_b128 v[192:195], v150 offset:35840
	ds_read_b128 v[196:199], v150 offset:36864
	ds_read_b128 v[200:203], v150 offset:37888
	ds_read_b128 v[204:207], v150 offset:38912
	ds_read_b128 v[208:211], v150 offset:39936
	global_load_lds_dwordx4 v136, s[28:29]
	s_mov_b32 m0, s37
	s_nop 0
	global_load_lds_dwordx4 v140, s[28:29]
	s_waitcnt vmcnt(8)
	s_waitcnt lgkmcnt(0)
	v_mfma_f32_16x16x32_bf16 v[132:135], v[52:55], v[180:183], v[132:135]
	v_mfma_f32_16x16x32_bf16 v[132:135], v[152:155], v[184:187], v[132:135]
	v_mfma_f32_16x16x32_bf16 v[128:131], v[160:163], v[184:187], v[128:131]
	v_mfma_f32_16x16x32_bf16 v[128:131], v[156:159], v[180:183], v[128:131]
	s_barrier
	s_setprio 1
	v_mfma_f32_16x16x32_bf16 v[120:123], v[156:159], v[188:191], v[120:123]
	v_mfma_f32_16x16x32_bf16 v[120:123], v[160:163], v[192:195], v[120:123]
	v_mfma_f32_16x16x32_bf16 v[124:127], v[152:155], v[192:195], v[124:127]
	v_mfma_f32_16x16x32_bf16 v[124:127], v[52:55], v[188:191], v[124:127]
	v_mfma_f32_16x16x32_bf16 v[108:111], v[52:55], v[196:199], v[108:111]
	v_mfma_f32_16x16x32_bf16 v[108:111], v[152:155], v[200:203], v[108:111]
	v_mfma_f32_16x16x32_bf16 v[104:107], v[160:163], v[200:203], v[104:107]
	v_mfma_f32_16x16x32_bf16 v[104:107], v[156:159], v[196:199], v[104:107]
	v_mfma_f32_16x16x32_bf16 v[88:91], v[156:159], v[204:207], v[88:91]
	v_mfma_f32_16x16x32_bf16 v[88:91], v[160:163], v[208:211], v[88:91]
	v_mfma_f32_16x16x32_bf16 v[92:95], v[152:155], v[208:211], v[92:95]
	v_mfma_f32_16x16x32_bf16 v[92:95], v[52:55], v[204:207], v[92:95]
	v_mfma_f32_16x16x32_bf16 v[76:79], v[164:167], v[204:207], v[76:79]
	v_mfma_f32_16x16x32_bf16 v[76:79], v[168:171], v[208:211], v[76:79]
	v_mfma_f32_16x16x32_bf16 v[116:119], v[168:171], v[184:187], v[116:119]
	v_mfma_f32_16x16x32_bf16 v[116:119], v[164:167], v[180:183], v[116:119]
	v_mfma_f32_16x16x32_bf16 v[112:115], v[172:175], v[180:183], v[112:115]
	v_mfma_f32_16x16x32_bf16 v[112:115], v[176:179], v[184:187], v[112:115]
	v_mfma_f32_16x16x32_bf16 v[96:99], v[176:179], v[192:195], v[96:99]
	v_mfma_f32_16x16x32_bf16 v[96:99], v[172:175], v[188:191], v[96:99]
	v_mfma_f32_16x16x32_bf16 v[100:103], v[164:167], v[188:191], v[100:103]
	v_mfma_f32_16x16x32_bf16 v[100:103], v[168:171], v[192:195], v[100:103]
	v_mfma_f32_16x16x32_bf16 v[84:87], v[168:171], v[200:203], v[84:87]
	v_mfma_f32_16x16x32_bf16 v[84:87], v[164:167], v[196:199], v[84:87]
	v_mfma_f32_16x16x32_bf16 v[80:83], v[172:175], v[196:199], v[80:83]
	v_mfma_f32_16x16x32_bf16 v[80:83], v[176:179], v[200:203], v[80:83]
	v_mfma_f32_16x16x32_bf16 v[72:75], v[176:179], v[208:211], v[72:75]
	v_mfma_f32_16x16x32_bf16 v[72:75], v[172:175], v[204:207], v[72:75]
	s_setprio 0
	s_barrier
; #define PG8_STAGE(bufoff, gbase, voff) do { _Pragma("unroll") for (int _i = 0; _i < 2; ++_i) \
;         __builtin_amdgcn_global_load_lds((const unsigned*)((const char*)(gbase) + (voff)[_i]), (PG8_LAS unsigned*)(lds + (bufoff) + ldsw + _i * 8192), 16, 0, 0); } while (0)
; #define PG8_LDA(dst, b, h) do { _Pragma("unroll") for (int m = 0; m < 4; ++m) _Pragma("unroll") for (int k = 0; k < 2; ++k) dst[m][k] = *(const PG8_LAS bf16x8*)(lds + PG8_SA(b, h) + aoff + m * 2048 + k * 1024); } while (0)
; #define PG8_MMA(ai, bj, At, Bt) do { __builtin_amdgcn_s_setprio(1); _Pragma("unroll") for (int m = 0; m < 4; ++m) _Pragma("unroll") for (int n = 0; n < 2; ++n) _Pragma("unroll") for (int k = 0; k < 2; ++k) \
;         acc[ai][bj][m][n] = __builtin_amdgcn_mfma_f32_16x16x32_bf16(Bt[n][k], At[m][k], acc[ai][bj][m][n], 0, 0, 0); __builtin_amdgcn_s_setprio(0); } while (0)
; #define PG8_WAIT_V(n) asm volatile("s_waitcnt vmcnt(" #n ")" ::: "memory")
; #define PG8_WAIT_L(n) asm volatile("s_waitcnt lgkmcnt(" #n ")" ::: "memory")
; #define PG8_BAR __builtin_amdgcn_s_barrier()
; #define PG8_SCHED __builtin_amdgcn_sched_barrier(0)
; template <class Epi, class Sched, bool ALIGN_EPI = false, bool SP2 = false, bool ABLK = false, bool BBLK = false>
; __device__ __forceinline__ void gemm_phase(PG8_LAS unsigned char* lds, const Gemm g, const Sched& S, const Epi& E) {
;     ...
;             PG8_LDA(At, 1, 1); PG8_STAGE(PG8_SB(1, 0), b3, voffB); PG8_STAGE(PG8_SB(1, 1), b3 + hstepB, voffB); PG8_STAGE(PG8_SA(1, 0), a3, voffA);
;             PG8_WAIT_V(8); PG8_WAIT_L(0); PG8_BAR; PG8_MMA(1, 0, At, B0); PG8_MMA(1, 1, At, B1); PG8_BAR; PG8_SCHED;
	s_add_u32 s28, s26, 0x8000
	s_addc_u32 s29, s27, 0
	s_add_i32 s68, s68, s34
	s_mov_b32 m0, s68
	ds_read_b128 v[180:183], v150 offset:49152
	ds_read_b128 v[184:187], v150 offset:50176
	ds_read_b128 v[188:191], v150 offset:51200
	ds_read_b128 v[192:195], v150 offset:52224
	ds_read_b128 v[196:199], v150 offset:53248
	ds_read_b128 v[200:203], v150 offset:54272
	ds_read_b128 v[204:207], v150 offset:55296
	ds_read_b128 v[208:211], v150 offset:56320
	global_load_lds_dwordx4 v138, s[28:29]
	s_add_i32 m0, s68, 0x2000
	s_add_u32 s26, s26, 0xc000
	s_addc_u32 s27, s27, 0
	global_load_lds_dwordx4 v142, s[28:29]
	s_add_i32 s28, s69, s34
	s_mov_b32 m0, s28
	s_nop 0
	global_load_lds_dwordx4 v138, s[26:27]
	s_add_i32 m0, s28, 0x2000
	s_nop 0
	global_load_lds_dwordx4 v142, s[26:27]
	s_mov_b32 m0, s64
	s_nop 0
	global_load_lds_dwordx4 v136, s[24:25]
	s_mov_b32 m0, s65
	s_nop 0
	global_load_lds_dwordx4 v140, s[24:25]
	s_waitcnt vmcnt(8)
	s_waitcnt lgkmcnt(0)
	v_mfma_f32_16x16x32_bf16 v[68:71], v[52:55], v[180:183], v[68:71]
	v_mfma_f32_16x16x32_bf16 v[68:71], v[152:155], v[184:187], v[68:71]
	v_mfma_f32_16x16x32_bf16 v[64:67], v[160:163], v[184:187], v[64:67]
	v_mfma_f32_16x16x32_bf16 v[64:67], v[156:159], v[180:183], v[64:67]
	s_barrier
	s_setprio 1
	v_mfma_f32_16x16x32_bf16 v[56:59], v[156:159], v[188:191], v[56:59]
	v_mfma_f32_16x16x32_bf16 v[56:59], v[160:163], v[192:195], v[56:59]
	v_mfma_f32_16x16x32_bf16 v[60:63], v[152:155], v[192:195], v[60:63]
	v_mfma_f32_16x16x32_bf16 v[60:63], v[52:55], v[188:191], v[60:63]
	v_mfma_f32_16x16x32_bf16 v[44:47], v[52:55], v[196:199], v[44:47]
	v_mfma_f32_16x16x32_bf16 v[44:47], v[152:155], v[200:203], v[44:47]
	v_mfma_f32_16x16x32_bf16 v[40:43], v[160:163], v[200:203], v[40:43]
	v_mfma_f32_16x16x32_bf16 v[40:43], v[156:159], v[196:199], v[40:43]
	v_mfma_f32_16x16x32_bf16 v[20:23], v[156:159], v[204:207], v[20:23]
	v_mfma_f32_16x16x32_bf16 v[20:23], v[160:163], v[208:211], v[20:23]
	v_mfma_f32_16x16x32_bf16 v[24:27], v[152:155], v[208:211], v[24:27]
	v_mfma_f32_16x16x32_bf16 v[24:27], v[52:55], v[204:207], v[24:27]
	v_mfma_f32_16x16x32_bf16 v[36:39], v[164:167], v[180:183], v[36:39]
	v_mfma_f32_16x16x32_bf16 v[52:55], v[168:171], v[184:187], v[36:39]
	v_mfma_f32_16x16x32_bf16 v[36:39], v[172:175], v[180:183], v[48:51]
	v_mfma_f32_16x16x32_bf16 v[32:35], v[164:167], v[188:191], v[32:35]
	v_mfma_f32_16x16x32_bf16 v[28:31], v[172:175], v[188:191], v[28:31]
	v_mfma_f32_16x16x32_bf16 v[16:19], v[164:167], v[196:199], v[16:19]
	v_mfma_f32_16x16x32_bf16 v[12:15], v[172:175], v[196:199], v[12:15]
	v_mfma_f32_16x16x32_bf16 v[8:11], v[164:167], v[204:207], v[8:11]
	v_mfma_f32_16x16x32_bf16 v[4:7], v[172:175], v[204:207], v[4:7]
	v_mfma_f32_16x16x32_bf16 v[48:51], v[176:179], v[184:187], v[36:39]
	v_mfma_f32_16x16x32_bf16 v[32:35], v[168:171], v[192:195], v[32:35]
	v_mfma_f32_16x16x32_bf16 v[28:31], v[176:179], v[192:195], v[28:31]
	v_mfma_f32_16x16x32_bf16 v[16:19], v[168:171], v[200:203], v[16:19]
	v_mfma_f32_16x16x32_bf16 v[12:15], v[176:179], v[200:203], v[12:15]
	v_mfma_f32_16x16x32_bf16 v[8:11], v[168:171], v[208:211], v[8:11]
	v_mfma_f32_16x16x32_bf16 v[4:7], v[176:179], v[208:211], v[4:7]
	s_setprio 0
	s_barrier
	s_add_i32 s13, s13, 2
	s_add_u32 s22, s22, 0x10000
	s_addc_u32 s23, s23, 0
	s_add_u32 s82, s82, 0x10000
	s_addc_u32 vcc_lo, vcc_lo, 0
	s_cmp_gt_u32 s13, 29
	s_cbranch_scc0 .LBB0_2111
	s_and_b64 vcc, exec, s[6:7]
	s_movk_i32 s77, 0x1000
	s_cbranch_vccz .LBB0_2114
	s_barrier
